# S5: load only the used half of the per-state decay constants so the waits in the middle of the fragment load bursts go away
# speedup vs baseline: 1.0080x; 1.0080x over previous
.LBB0_280:
	s_and_b32 s4, s17, 8
	v_mov_b64_e32 v[4:5], s[0:1]
	s_add_i32 s4, s4, s11
	v_mad_i64_i32 v[2:3], s[0:1], v2, s94, v[4:5]
	s_lshl_b32 s0, s4, 4
	s_ashr_i32 s1, s0, 31
	s_lshr_b32 s5, s6, 6
	v_lshl_add_u64 v[2:3], s[0:1], 1, v[2:3]
	s_mov_b64 s[6:7], 0xe001000
	v_lshl_add_u64 v[6:7], v[2:3], 0, s[6:7]
	v_add_co_u32_e32 v2, vcc, 0xe001000, v2
	s_mulk_i32 s5, 0x3e00
	s_nop 0
	v_addc_co_u32_e32 v3, vcc, 0, v3, vcc
	global_load_dwordx4 v[2:5], v[2:3], off
	s_nop 0
	global_load_dwordx4 v[6:9], v[6:7], off offset:16
	s_add_i32 s5, s5, 0
	v_mad_u32_u24 v0, v0, 48, s5
	v_mov_b32_e32 v62, v204
	s_add_i32 s6, s4, s21
	s_ashr_i32 s7, s6, 31
	s_lshl_b64 s[26:27], s[6:7], 13
	s_waitcnt vmcnt(0) lgkmcnt(0)
	ds_write_b128 v0, v[2:5]
	ds_write_b128 v0, v[6:9] offset:16
	v_mov_b32_e32 v0, s59
	s_waitcnt lgkmcnt(0)
	ds_read_b64 v[2:3], v0
	v_and_b32_e32 v61, 63, v62
	v_readfirstlane_b32 s5, v62
	s_lshr_b32 s5, s5, 6
	s_mulk_i32 s5, 0x3e00
	s_waitcnt lgkmcnt(0)
	v_readfirstlane_b32 s8, v2
	v_lshl_or_b32 v2, s6, 6, v61
	v_readfirstlane_b32 s9, v3
	v_ashrrev_i32_e32 v3, 31, v2
	s_add_i32 s28, s5, 0
	v_lshl_add_u64 v[2:3], v[2:3], 4, s[8:9]
	s_mov_b32 s5, 0x200000
	v_add_co_u32_e32 v2, vcc, s5, v2
	s_add_u32 s26, s8, s26
	v_and_b32_e32 v60, 15, v62
	v_addc_co_u32_e32 v3, vcc, 0, v3, vcc
	s_addc_u32 s27, s9, s27
	v_and_b32_e32 v0, 48, v62
	global_load_dwordx2 v[6:7], v[2:3], off
	v_lshl_add_u64 v[2:3], s[26:27], 0, v[0:1]
	v_lshlrev_b32_e32 v4, 6, v60
	v_mov_b32_e32 v5, v1
	v_lshl_add_u64 v[2:3], v[2:3], 0, v[4:5]
	s_mov_b32 s5, 0x240000
	s_waitcnt lgkmcnt(0)
	v_add_co_u32_e32 v8, vcc, s5, v2
	s_mov_b64 s[26:27], 0x240000
	s_nop 0
	v_addc_co_u32_e32 v9, vcc, 0, v3, vcc
	s_mov_b32 s5, 0x241000
	v_lshl_add_u64 v[4:5], v[2:3], 0, s[26:27]
	v_add_co_u32_e32 v2, vcc, s5, v2
	s_lshl_b64 s[6:7], s[6:7], 12
	s_nop 0
	v_addc_co_u32_e32 v3, vcc, 0, v3, vcc
	s_add_u32 s6, s8, s6
	global_load_dwordx4 v[52:55], v[8:9], off
	global_load_dwordx4 v[56:59], v[4:5], off offset:1024
	global_load_dwordx4 v[44:47], v[4:5], off offset:2048
	global_load_dwordx4 v[48:51], v[4:5], off offset:3072
	global_load_dwordx4 v[40:43], v[2:3], off
	global_load_dwordx4 v[36:39], v[2:3], off offset:1024
	global_load_dwordx4 v[32:35], v[2:3], off offset:2048
	global_load_dwordx4 v[28:31], v[2:3], off offset:3072
	s_addc_u32 s7, s9, s7
	v_lshlrev_b32_e32 v2, 8, v60
	v_mov_b32_e32 v3, v1
	v_lshl_add_u64 v[2:3], s[6:7], 0, v[2:3]
	v_lshl_add_u64 v[2:3], v[2:3], 0, v[0:1]
	s_mov_b64 s[6:7], 0x380000
	v_lshl_add_u64 v[4:5], v[2:3], 0, s[6:7]
	s_mov_b32 s5, 0x380000
	s_lshl_b32 s26, s20, 1
	s_mul_i32 s6, s20, 0x88
	s_ashr_i32 s27, s22, 31
	v_add_co_u32_e32 v2, vcc, s5, v2
	s_mul_hi_i32 s5, s26, 0x44
	s_add_u32 s6, s6, s22
	s_addc_u32 s7, s5, s27
	s_ashr_i32 s5, s4, 31
	s_lshl_b64 s[38:39], s[6:7], 10
	s_lshl_b64 s[6:7], s[4:5], 6
	s_add_u32 s5, s38, s6
	v_addc_co_u32_e32 v3, vcc, 0, v3, vcc
	s_addc_u32 s29, s39, s7
	global_load_dwordx4 v[24:27], v[2:3], off
	global_load_dwordx4 v[20:23], v[4:5], off offset:64
	global_load_dwordx4 v[16:19], v[4:5], off offset:128
	global_load_dwordx4 v[12:15], v[4:5], off offset:192
	v_or_b32_e32 v2, s5, v61
	v_mov_b32_e32 v3, s29
	v_lshl_add_u64 v[2:3], v[2:3], 3, s[8:9]
	v_add_co_u32_e32 v2, vcc, 0x1500000, v2
	v_mov_b32_e32 v8, 0
	s_nop 0
	v_addc_co_u32_e32 v3, vcc, 0, v3, vcc
	global_load_dwordx2 v[10:11], v[2:3], off
	v_add_u32_e32 v2, s28, v0
	v_cmp_gt_u32_e32 vcc, 32, v61
	v_mad_u32_u24 v95, v60, 48, v2
	v_mov_b32_e32 v2, 0
	v_mov_b32_e32 v3, 0
	v_mov_b32_e32 v4, 0
	v_mov_b32_e32 v5, 0
	s_and_saveexec_b64 s[8:9], vcc
	ds_read_b128 v[2:5], v95
	s_or_b64 exec, exec, s[8:9]
	s_waitcnt vmcnt(0) lgkmcnt(0)
	v_mfma_f32_16x16x32_bf16 v[64:67], v[2:5], v[52:55], 0
	v_bfe_u32 v9, v62, 4, 2
	v_lshlrev_b32_e32 v79, 2, v61
	v_mov_b32_e32 v61, s28
	v_mfma_f32_16x16x32_bf16 v[70:73], v[2:5], v[56:59], 0
	s_movk_i32 s5, 0x110
	v_lshlrev_b32_e32 v68, 2, v60
	v_mad_u32_u24 v112, v60, s5, v61
	v_mul_u32_u24_e32 v9, 0x840, v9
	v_mfma_f32_16x16x32_bf16 v[60:63], v[2:5], v[44:47], 0
	v_add3_u32 v9, s28, v68, v9
	v_add_u32_e32 v68, 0xc00, v9
	v_add_u32_e32 v69, 0x1000, v9
	v_mfma_f32_16x16x32_bf16 v[74:77], v[2:5], v[48:51], 0
	ds_write2_b32 v68, v64, v70 offset1:16
	ds_write2_b32 v68, v65, v71 offset0:132 offset1:148
	ds_write2_b32 v69, v66, v72 offset0:8 offset1:24
	v_mfma_f32_16x16x32_bf16 v[80:83], v[2:5], v[40:43], 0
	ds_write2_b32 v69, v67, v73 offset0:140 offset1:156
	s_nop 2
	ds_write2_b32 v68, v60, v74 offset0:32 offset1:48
	ds_write2_b32 v68, v61, v75 offset0:164 offset1:180
	v_add_u32_e32 v70, s28, v79
	v_mul_f32_e32 v9, v7, v11
	v_mfma_f32_16x16x32_bf16 v[64:67], v[2:5], v[36:39], 0
	ds_write2_b32 v69, v62, v76 offset0:40 offset1:56
	ds_write2_b32 v69, v63, v77 offset0:172 offset1:188
	s_nop 5
	ds_write2_b32 v68, v80, v64 offset0:64 offset1:80
	ds_write2_b32 v68, v81, v65 offset0:196 offset1:212
	ds_write2_b32 v69, v82, v66 offset0:72 offset1:88
	ds_write2_b32 v69, v83, v67 offset0:204 offset1:220
	v_mfma_f32_16x16x32_bf16 v[60:63], v[2:5], v[32:35], 0
	v_add_u32_e32 v71, 16, v70
	v_fma_f32 v9, v6, v10, -v9
	v_add_u32_e32 v72, 32, v70
	v_mfma_f32_16x16x32_bf16 v[2:5], v[2:5], v[28:31], 0
	s_nop 7
	ds_write2_b32 v68, v60, v2 offset0:96 offset1:112
	ds_write2_b32 v68, v61, v3 offset0:228 offset1:244
	ds_write2_b32 v69, v62, v4 offset0:104 offset1:120
	ds_write2_b32 v69, v63, v5 offset0:236 offset1:252
	s_waitcnt lgkmcnt(0)
	ds_read2st64_b32 v[2:3], v70 offset0:12 offset1:13
	ds_read2st64_b32 v[4:5], v71 offset0:14 offset1:15
	ds_read2st64_b32 v[60:61], v72 offset0:16 offset1:17
	v_add_u32_e32 v87, 0x2c00, v70
	v_add_u32_e32 v73, 48, v70
	s_waitcnt lgkmcnt(2)
	v_add_f32_e32 v2, v9, v2
	v_mul_f32_e32 v9, v7, v10
	v_fmac_f32_e32 v9, v6, v11
	v_add_f32_e32 v3, v9, v3
	v_cvt_pk_bf16_f32 v9, v2, v3
	s_waitcnt lgkmcnt(1)
	v_fma_f32 v10, v7, v2, v5
	v_fma_f32 v4, v6, v2, v4
	v_fma_f32 v4, -v7, v3, v4
	v_fma_f32 v2, v6, v3, v10
	v_cvt_pk_bf16_f32 v3, v4, v2
	ds_write2_b32 v87, v9, v3 offset0:64 offset1:132
	ds_read2st64_b32 v[62:63], v73 offset0:18 offset1:19
	s_waitcnt lgkmcnt(2)
	v_fma_f32 v3, -v2, v7, v60
	v_fma_f32 v2, v2, v6, v61
	v_fma_f32 v2, v4, v7, v2
	v_fma_f32 v3, v4, v6, v3
	v_add_u32_e32 v74, 64, v70
	v_cvt_pk_bf16_f32 v4, v3, v2
	ds_read2st64_b32 v[64:65], v74 offset0:20 offset1:21
	s_waitcnt lgkmcnt(1)
	v_fma_f32 v5, -v2, v7, v62
	v_fma_f32 v2, v2, v6, v63
	v_fma_f32 v2, v3, v7, v2
	v_fma_f32 v5, v3, v6, v5
	v_cvt_pk_bf16_f32 v3, v5, v2
	v_add_u32_e32 v88, 0x2e00, v70
	v_add_u32_e32 v75, 0x50, v70
	ds_write2_b32 v88, v4, v3 offset0:72 offset1:140
	ds_read2st64_b32 v[66:67], v75 offset0:22 offset1:23
	s_waitcnt lgkmcnt(2)
	v_fma_f32 v4, v7, v5, v65
	v_fma_f32 v3, v6, v5, v64
	v_fma_f32 v3, -v7, v2, v3
	v_fma_f32 v2, v6, v2, v4
	v_add_u32_e32 v76, 0x60, v70
	v_cvt_pk_bf16_f32 v4, v3, v2
	ds_read2st64_b32 v[90:91], v76 offset0:24 offset1:25
	s_waitcnt lgkmcnt(1)
	v_fma_f32 v5, -v2, v7, v66
	v_fma_f32 v2, v2, v6, v67
	v_fma_f32 v2, v3, v7, v2
	v_fma_f32 v5, v3, v6, v5
	v_cvt_pk_bf16_f32 v3, v5, v2
	v_add_u32_e32 v89, 0x3000, v70
	v_add_u32_e32 v77, 0x70, v70
	ds_write2_b32 v89, v4, v3 offset0:80 offset1:148
	ds_read2st64_b32 v[92:93], v77 offset0:26 offset1:27
	s_waitcnt lgkmcnt(2)
	v_fma_f32 v4, v7, v5, v91
	v_fma_f32 v3, v6, v5, v90
	v_fma_f32 v3, -v7, v2, v3
	v_fma_f32 v2, v6, v2, v4
	v_add_u32_e32 v79, 0x80, v70
	v_cvt_pk_bf16_f32 v4, v3, v2
	ds_read2st64_b32 v[96:97], v79 offset0:28 offset1:29
	s_waitcnt lgkmcnt(1)
	v_fma_f32 v5, -v2, v7, v92
	v_fma_f32 v2, v2, v6, v93
	v_fma_f32 v2, v3, v7, v2
	v_fma_f32 v5, v3, v6, v5
	v_cvt_pk_bf16_f32 v3, v5, v2
	v_add_u32_e32 v90, 0x3200, v70
	v_add_u32_e32 v80, 0x90, v70
	ds_write2_b32 v90, v4, v3 offset0:88 offset1:156
	ds_read2st64_b32 v[98:99], v80 offset0:30 offset1:31
	s_waitcnt lgkmcnt(2)
	v_fma_f32 v4, v7, v5, v97
	v_fma_f32 v3, v6, v5, v96
	v_fma_f32 v3, -v7, v2, v3
	v_fma_f32 v2, v6, v2, v4
	v_add_u32_e32 v81, 0xa0, v70
	v_cvt_pk_bf16_f32 v4, v3, v2
	ds_read2st64_b32 v[100:101], v81 offset0:32 offset1:33
	s_waitcnt lgkmcnt(1)
	v_fma_f32 v5, -v2, v7, v98
	v_fma_f32 v2, v2, v6, v99
	v_fma_f32 v2, v3, v7, v2
	v_fma_f32 v5, v3, v6, v5
	v_cvt_pk_bf16_f32 v3, v5, v2
	v_add_u32_e32 v91, 0x3400, v70
	v_add_u32_e32 v82, 0xb0, v70
	ds_write2_b32 v91, v4, v3 offset0:96 offset1:164
	ds_read2st64_b32 v[102:103], v82 offset0:34 offset1:35
	s_waitcnt lgkmcnt(2)
	v_fma_f32 v4, v7, v5, v101
	v_fma_f32 v3, v6, v5, v100
	v_fma_f32 v3, -v7, v2, v3
	v_fma_f32 v2, v6, v2, v4
	v_add_u32_e32 v83, 0xc0, v70
	v_cvt_pk_bf16_f32 v4, v3, v2
	ds_read2st64_b32 v[104:105], v83 offset0:36 offset1:37
	s_waitcnt lgkmcnt(1)
	v_fma_f32 v5, -v2, v7, v102
	v_fma_f32 v2, v2, v6, v103
	v_fma_f32 v2, v3, v7, v2
	v_fma_f32 v5, v3, v6, v5
	v_cvt_pk_bf16_f32 v3, v5, v2
	v_add_u32_e32 v92, 0x3600, v70
	v_add_u32_e32 v84, 0xd0, v70
	ds_write2_b32 v92, v4, v3 offset0:104 offset1:172
	ds_read2st64_b32 v[106:107], v84 offset0:38 offset1:39
	s_waitcnt lgkmcnt(2)
	v_fma_f32 v4, v7, v5, v105
	v_fma_f32 v3, v6, v5, v104
	v_fma_f32 v3, -v7, v2, v3
	v_fma_f32 v2, v6, v2, v4
	v_add_u32_e32 v85, 0xe0, v70
	v_cvt_pk_bf16_f32 v4, v3, v2
	ds_read2st64_b32 v[108:109], v85 offset0:40 offset1:41
	s_waitcnt lgkmcnt(1)
	v_fma_f32 v5, -v2, v7, v106
	v_fma_f32 v2, v2, v6, v107
	v_fma_f32 v2, v3, v7, v2
	v_fma_f32 v5, v3, v6, v5
	v_cvt_pk_bf16_f32 v3, v5, v2
	v_add_u32_e32 v93, 0x3800, v70
	v_add_u32_e32 v86, 0xf0, v70
	ds_write2_b32 v93, v4, v3 offset0:112 offset1:180
	ds_read2st64_b32 v[110:111], v86 offset0:42 offset1:43
	s_waitcnt lgkmcnt(2)
	v_fma_f32 v4, v7, v5, v109
	v_fma_f32 v3, v6, v5, v108
	v_fma_f32 v3, -v7, v2, v3
	v_fma_f32 v2, v6, v2, v4
	v_cvt_pk_bf16_f32 v4, v3, v2
	s_waitcnt lgkmcnt(0)
	v_fma_f32 v5, v7, v3, v111
	v_fma_f32 v60, v6, v3, v110
	v_fma_f32 v60, -v7, v2, v60
	v_fma_f32 v61, v6, v2, v5
	v_cvt_pk_bf16_f32 v2, v60, v61
	v_add_u32_e32 v94, 0x3a00, v70
	ds_write2_b32 v94, v4, v2 offset0:120 offset1:188
	s_waitcnt lgkmcnt(0)
	v_add_u32_e32 v0, v112, v0
	ds_read_b128 v[2:5], v0 offset:11520
	ds_read_b128 v[62:65], v0 offset:11584
	s_waitcnt lgkmcnt(1)
	v_mfma_f32_16x16x32_bf16 v[2:5], v[2:5], v[24:27], 0
	ds_read_b128 v[96:99], v0 offset:11648
	v_mov_b32_e32 v9, 0
	v_mov_b32_e32 v10, 0
	s_waitcnt lgkmcnt(1)
	v_mfma_f32_16x16x32_bf16 v[2:5], v[62:65], v[20:23], v[2:5]
	ds_read_b128 v[62:65], v0 offset:11712
	v_mov_b32_e32 v11, 0
	s_waitcnt lgkmcnt(1)
	v_mfma_f32_16x16x32_bf16 v[2:5], v[96:99], v[16:19], v[2:5]
	s_waitcnt lgkmcnt(0)
	v_mfma_f32_16x16x32_bf16 v[2:5], v[62:65], v[12:15], v[2:5]
	s_and_saveexec_b64 s[8:9], vcc
	ds_read_b128 v[8:11], v95 offset:768
	s_or_b64 exec, exec, s[8:9]
	s_waitcnt lgkmcnt(0)
	v_mfma_f32_16x16x32_bf16 v[62:65], v[8:11], v[52:55], 0
	v_mul_f32_e32 v118, v7, v61
	v_fma_f32 v118, v6, v60, -v118
	v_mul_f32_e32 v60, v7, v60
	v_mfma_f32_16x16x32_bf16 v[96:99], v[8:11], v[56:59], 0
	s_nop 7
	ds_write2_b32 v68, v62, v96 offset1:16
	ds_write2_b32 v68, v63, v97 offset0:132 offset1:148
	ds_write2_b32 v69, v64, v98 offset0:8 offset1:24
	v_mfma_f32_16x16x32_bf16 v[100:103], v[8:11], v[44:47], 0
	v_fmac_f32_e32 v60, v6, v61
	v_mfma_f32_16x16x32_bf16 v[104:107], v[8:11], v[48:51], 0
	ds_write2_b32 v69, v65, v99 offset0:140 offset1:156
	s_nop 6
	ds_write2_b32 v68, v100, v104 offset0:32 offset1:48
	ds_write2_b32 v68, v101, v105 offset0:164 offset1:180
	v_mfma_f32_16x16x32_bf16 v[108:111], v[8:11], v[40:43], 0
	v_mfma_f32_16x16x32_bf16 v[62:65], v[8:11], v[36:39], 0
	ds_write2_b32 v69, v102, v106 offset0:40 offset1:56
	ds_write2_b32 v69, v103, v107 offset0:172 offset1:188
	s_nop 5
	ds_write2_b32 v68, v108, v62 offset0:64 offset1:80
	ds_write2_b32 v68, v109, v63 offset0:196 offset1:212
	ds_write2_b32 v69, v110, v64 offset0:72 offset1:88
	ds_write2_b32 v69, v111, v65 offset0:204 offset1:220
	v_mfma_f32_16x16x32_bf16 v[96:99], v[8:11], v[32:35], 0
	v_mfma_f32_16x16x32_bf16 v[8:11], v[8:11], v[28:31], 0
	s_nop 7
	ds_write2_b32 v68, v96, v8 offset0:96 offset1:112
	ds_write2_b32 v68, v97, v9 offset0:228 offset1:244
	ds_write2_b32 v69, v98, v10 offset0:104 offset1:120
	ds_write2_b32 v69, v99, v11 offset0:236 offset1:252
	s_waitcnt lgkmcnt(0)
	ds_read2st64_b32 v[8:9], v70 offset0:12 offset1:13
	ds_read2st64_b32 v[10:11], v71 offset0:14 offset1:15
	ds_read2st64_b32 v[62:63], v72 offset0:16 offset1:17
	ds_read2st64_b32 v[64:65], v73 offset0:18 offset1:19
	ds_read2st64_b32 v[66:67], v74 offset0:20 offset1:21
	ds_read2st64_b32 v[96:97], v75 offset0:22 offset1:23
	ds_read2st64_b32 v[98:99], v76 offset0:24 offset1:25
	ds_read2st64_b32 v[100:101], v77 offset0:26 offset1:27
	ds_read2st64_b32 v[102:103], v79 offset0:28 offset1:29
	ds_read2st64_b32 v[104:105], v80 offset0:30 offset1:31
	ds_read2st64_b32 v[106:107], v81 offset0:32 offset1:33
	ds_read2st64_b32 v[108:109], v82 offset0:34 offset1:35
	ds_read2st64_b32 v[110:111], v83 offset0:36 offset1:37
	ds_read2st64_b32 v[112:113], v84 offset0:38 offset1:39
	ds_read2st64_b32 v[114:115], v85 offset0:40 offset1:41
	ds_read2st64_b32 v[116:117], v86 offset0:42 offset1:43
	s_waitcnt lgkmcnt(14)
	v_add_f32_e32 v8, v118, v8
	v_add_f32_e32 v9, v60, v9
	v_cvt_pk_bf16_f32 v60, v8, v9
	v_fma_f32 v61, v7, v8, v11
	v_fma_f32 v10, v6, v8, v10
	v_fma_f32 v10, -v7, v9, v10
	v_fma_f32 v8, v6, v9, v61
	v_cvt_pk_bf16_f32 v9, v10, v8
	ds_write2_b32 v87, v60, v9 offset0:64 offset1:132
	s_waitcnt lgkmcnt(14)
	v_fma_f32 v9, -v8, v7, v62
	v_fma_f32 v8, v8, v6, v63
	v_fma_f32 v8, v10, v7, v8
	v_fma_f32 v9, v10, v6, v9
	v_cvt_pk_bf16_f32 v10, v9, v8
	s_waitcnt lgkmcnt(13)
	v_fma_f32 v11, -v8, v7, v64
	v_fma_f32 v8, v8, v6, v65
	v_fma_f32 v8, v9, v7, v8
	v_fma_f32 v11, v9, v6, v11
	v_cvt_pk_bf16_f32 v9, v11, v8
	ds_write2_b32 v88, v10, v9 offset0:72 offset1:140
	s_waitcnt lgkmcnt(13)
	v_fma_f32 v10, v7, v11, v67
	v_fma_f32 v9, v6, v11, v66
	v_fma_f32 v9, -v7, v8, v9
	v_fma_f32 v8, v6, v8, v10
	v_cvt_pk_bf16_f32 v10, v9, v8
	s_waitcnt lgkmcnt(12)
	v_fma_f32 v11, -v8, v7, v96
	v_fma_f32 v8, v8, v6, v97
	v_fma_f32 v8, v9, v7, v8
	v_fma_f32 v11, v9, v6, v11
	v_cvt_pk_bf16_f32 v9, v11, v8
	ds_write2_b32 v89, v10, v9 offset0:80 offset1:148
	s_waitcnt lgkmcnt(12)
	v_fma_f32 v10, v7, v11, v99
	v_fma_f32 v9, v6, v11, v98
	v_fma_f32 v9, -v7, v8, v9
	v_fma_f32 v8, v6, v8, v10
	v_cvt_pk_bf16_f32 v10, v9, v8
	s_waitcnt lgkmcnt(11)
	v_fma_f32 v11, -v8, v7, v100
	v_fma_f32 v8, v8, v6, v101
	v_fma_f32 v8, v9, v7, v8
	v_fma_f32 v11, v9, v6, v11
	v_cvt_pk_bf16_f32 v9, v11, v8
	ds_write2_b32 v90, v10, v9 offset0:88 offset1:156
	s_waitcnt lgkmcnt(11)
	v_fma_f32 v10, v7, v11, v103
	v_fma_f32 v9, v6, v11, v102
	v_fma_f32 v9, -v7, v8, v9
	v_fma_f32 v8, v6, v8, v10
	v_cvt_pk_bf16_f32 v10, v9, v8
	s_waitcnt lgkmcnt(10)
	v_fma_f32 v11, -v8, v7, v104
	v_fma_f32 v8, v8, v6, v105
	v_fma_f32 v8, v9, v7, v8
	v_fma_f32 v11, v9, v6, v11
	v_cvt_pk_bf16_f32 v9, v11, v8
	ds_write2_b32 v91, v10, v9 offset0:96 offset1:164
	s_waitcnt lgkmcnt(10)
	v_fma_f32 v10, v7, v11, v107
	v_fma_f32 v9, v6, v11, v106
	v_fma_f32 v9, -v7, v8, v9
	v_fma_f32 v8, v6, v8, v10
	v_cvt_pk_bf16_f32 v10, v9, v8
	s_waitcnt lgkmcnt(9)
	v_fma_f32 v11, -v8, v7, v108
	v_fma_f32 v8, v8, v6, v109
	v_fma_f32 v8, v9, v7, v8
	v_fma_f32 v11, v9, v6, v11
	v_cvt_pk_bf16_f32 v9, v11, v8
	ds_write2_b32 v92, v10, v9 offset0:104 offset1:172
	s_waitcnt lgkmcnt(9)
	v_fma_f32 v10, v7, v11, v111
	v_fma_f32 v9, v6, v11, v110
	v_fma_f32 v9, -v7, v8, v9
	v_fma_f32 v8, v6, v8, v10
	v_cvt_pk_bf16_f32 v10, v9, v8
	s_waitcnt lgkmcnt(8)
	v_fma_f32 v11, -v8, v7, v112
	v_fma_f32 v8, v8, v6, v113
	v_fma_f32 v8, v9, v7, v8
	v_fma_f32 v11, v9, v6, v11
	v_cvt_pk_bf16_f32 v9, v11, v8
	ds_write2_b32 v93, v10, v9 offset0:112 offset1:180
	s_waitcnt lgkmcnt(8)
	v_fma_f32 v10, v7, v11, v115
	v_fma_f32 v9, v6, v11, v114
	v_fma_f32 v9, -v7, v8, v9
	v_fma_f32 v8, v6, v8, v10
	v_cvt_pk_bf16_f32 v10, v9, v8
	s_waitcnt lgkmcnt(7)
	v_fma_f32 v11, v7, v9, v117
	v_fma_f32 v65, v6, v9, v116
	v_fma_f32 v65, -v7, v8, v65
	v_fma_f32 v66, v6, v8, v11
	v_cvt_pk_bf16_f32 v8, v65, v66
	ds_write2_b32 v94, v10, v8 offset0:120 offset1:188
	s_waitcnt lgkmcnt(0)
	ds_read_b128 v[8:11], v0 offset:11520
	ds_read_b128 v[60:63], v0 offset:11584
	s_waitcnt lgkmcnt(1)
	v_mfma_f32_16x16x32_bf16 v[8:11], v[8:11], v[24:27], 0
	ds_read_b128 v[96:99], v0 offset:11648
	v_mov_b32_e32 v64, 0
	s_waitcnt lgkmcnt(1)
	v_mfma_f32_16x16x32_bf16 v[8:11], v[60:63], v[20:23], v[8:11]
	ds_read_b128 v[60:63], v0 offset:11712
	s_waitcnt lgkmcnt(1)
	v_mfma_f32_16x16x32_bf16 v[8:11], v[96:99], v[16:19], v[8:11]
	s_waitcnt lgkmcnt(0)
	v_mfma_f32_16x16x32_bf16 v[8:11], v[60:63], v[12:15], v[8:11]
	v_mov_b32_e32 v60, 0
	v_mov_b32_e32 v61, 0
	v_mov_b32_e32 v62, 0
	v_mov_b32_e32 v63, 0
	s_and_saveexec_b64 s[8:9], vcc
	ds_read_b128 v[60:63], v95 offset:1536
	s_or_b64 exec, exec, s[8:9]
	s_waitcnt lgkmcnt(0)
	v_mfma_f32_16x16x32_bf16 v[96:99], v[60:63], v[52:55], 0
	v_mul_f32_e32 v67, v7, v66
	v_fma_f32 v67, v6, v65, -v67
	v_mul_f32_e32 v65, v7, v65
	v_mfma_f32_16x16x32_bf16 v[100:103], v[60:63], v[56:59], 0
	s_nop 7
	ds_write2_b32 v68, v96, v100 offset1:16
	ds_write2_b32 v68, v97, v101 offset0:132 offset1:148
	ds_write2_b32 v69, v98, v102 offset0:8 offset1:24
	v_mfma_f32_16x16x32_bf16 v[104:107], v[60:63], v[44:47], 0
	v_fmac_f32_e32 v65, v6, v66
	v_mfma_f32_16x16x32_bf16 v[108:111], v[60:63], v[48:51], 0
	ds_write2_b32 v69, v99, v103 offset0:140 offset1:156
	s_nop 6
	ds_write2_b32 v68, v104, v108 offset0:32 offset1:48
	ds_write2_b32 v68, v105, v109 offset0:164 offset1:180
	v_mfma_f32_16x16x32_bf16 v[112:115], v[60:63], v[40:43], 0
	v_mfma_f32_16x16x32_bf16 v[96:99], v[60:63], v[36:39], 0
	ds_write2_b32 v69, v106, v110 offset0:40 offset1:56
	ds_write2_b32 v69, v107, v111 offset0:172 offset1:188
	s_nop 5
	ds_write2_b32 v68, v112, v96 offset0:64 offset1:80
	ds_write2_b32 v68, v113, v97 offset0:196 offset1:212
	ds_write2_b32 v69, v114, v98 offset0:72 offset1:88
	ds_write2_b32 v69, v115, v99 offset0:204 offset1:220
	v_mfma_f32_16x16x32_bf16 v[100:103], v[60:63], v[32:35], 0
	v_mfma_f32_16x16x32_bf16 v[60:63], v[60:63], v[28:31], 0
	s_nop 7
	ds_write2_b32 v68, v100, v60 offset0:96 offset1:112
	ds_write2_b32 v68, v101, v61 offset0:228 offset1:244
	ds_write2_b32 v69, v102, v62 offset0:104 offset1:120
	ds_write2_b32 v69, v103, v63 offset0:236 offset1:252
	s_waitcnt lgkmcnt(0)
	ds_read2st64_b32 v[60:61], v70 offset0:12 offset1:13
	ds_read2st64_b32 v[62:63], v71 offset0:14 offset1:15
	ds_read2st64_b32 v[96:97], v72 offset0:16 offset1:17
	ds_read2st64_b32 v[98:99], v73 offset0:18 offset1:19
	ds_read2st64_b32 v[100:101], v74 offset0:20 offset1:21
	ds_read2st64_b32 v[102:103], v75 offset0:22 offset1:23
	ds_read2st64_b32 v[104:105], v76 offset0:24 offset1:25
	ds_read2st64_b32 v[106:107], v77 offset0:26 offset1:27
	ds_read2st64_b32 v[108:109], v79 offset0:28 offset1:29
	ds_read2st64_b32 v[110:111], v80 offset0:30 offset1:31
	ds_read2st64_b32 v[112:113], v81 offset0:32 offset1:33
	ds_read2st64_b32 v[114:115], v82 offset0:34 offset1:35
	ds_read2st64_b32 v[116:117], v83 offset0:36 offset1:37
	ds_read2st64_b32 v[118:119], v84 offset0:38 offset1:39
	ds_read2st64_b32 v[120:121], v85 offset0:40 offset1:41
	ds_read2st64_b32 v[122:123], v86 offset0:42 offset1:43
	s_waitcnt lgkmcnt(14)
	v_add_f32_e32 v60, v67, v60
	v_add_f32_e32 v61, v65, v61
	v_cvt_pk_bf16_f32 v65, v60, v61
	v_fma_f32 v66, v7, v60, v63
	v_fma_f32 v62, v6, v60, v62
	v_fma_f32 v62, -v7, v61, v62
	v_fma_f32 v60, v6, v61, v66
	v_cvt_pk_bf16_f32 v61, v62, v60
	ds_write2_b32 v87, v65, v61 offset0:64 offset1:132
	s_waitcnt lgkmcnt(14)
	v_fma_f32 v61, -v60, v7, v96
	v_fma_f32 v60, v60, v6, v97
	v_fma_f32 v60, v62, v7, v60
	v_fma_f32 v61, v62, v6, v61
	v_cvt_pk_bf16_f32 v62, v61, v60
	s_waitcnt lgkmcnt(13)
	v_fma_f32 v63, -v60, v7, v98
	v_fma_f32 v60, v60, v6, v99
	v_fma_f32 v60, v61, v7, v60
	v_fma_f32 v63, v61, v6, v63
	v_cvt_pk_bf16_f32 v61, v63, v60
	ds_write2_b32 v88, v62, v61 offset0:72 offset1:140
	s_waitcnt lgkmcnt(13)
	v_fma_f32 v62, v7, v63, v101
	v_fma_f32 v61, v6, v63, v100
	v_fma_f32 v61, -v7, v60, v61
	v_fma_f32 v60, v6, v60, v62
	v_cvt_pk_bf16_f32 v62, v61, v60
	s_waitcnt lgkmcnt(12)
	v_fma_f32 v63, -v60, v7, v102
	v_fma_f32 v60, v60, v6, v103
	v_fma_f32 v60, v61, v7, v60
	v_fma_f32 v63, v61, v6, v63
	v_cvt_pk_bf16_f32 v61, v63, v60
	ds_write2_b32 v89, v62, v61 offset0:80 offset1:148
	s_waitcnt lgkmcnt(12)
	v_fma_f32 v62, v7, v63, v105
	v_fma_f32 v61, v6, v63, v104
	v_fma_f32 v61, -v7, v60, v61
	v_fma_f32 v60, v6, v60, v62
	v_cvt_pk_bf16_f32 v62, v61, v60
	s_waitcnt lgkmcnt(11)
	v_fma_f32 v63, -v60, v7, v106
	v_fma_f32 v60, v60, v6, v107
	v_fma_f32 v60, v61, v7, v60
	v_fma_f32 v63, v61, v6, v63
	v_cvt_pk_bf16_f32 v61, v63, v60
	ds_write2_b32 v90, v62, v61 offset0:88 offset1:156
	s_waitcnt lgkmcnt(11)
	v_fma_f32 v62, v7, v63, v109
	v_fma_f32 v61, v6, v63, v108
	v_fma_f32 v61, -v7, v60, v61
	v_fma_f32 v60, v6, v60, v62
	v_cvt_pk_bf16_f32 v62, v61, v60
	s_waitcnt lgkmcnt(10)
	v_fma_f32 v63, -v60, v7, v110
	v_fma_f32 v60, v60, v6, v111
	v_fma_f32 v60, v61, v7, v60
	v_fma_f32 v63, v61, v6, v63
	v_cvt_pk_bf16_f32 v61, v63, v60
	ds_write2_b32 v91, v62, v61 offset0:96 offset1:164
	s_waitcnt lgkmcnt(10)
	v_fma_f32 v62, v7, v63, v113
	v_fma_f32 v61, v6, v63, v112
	v_fma_f32 v61, -v7, v60, v61
	v_fma_f32 v60, v6, v60, v62
	v_cvt_pk_bf16_f32 v62, v61, v60
	s_waitcnt lgkmcnt(9)
	v_fma_f32 v63, -v60, v7, v114
	v_fma_f32 v60, v60, v6, v115
	v_fma_f32 v60, v61, v7, v60
	v_fma_f32 v63, v61, v6, v63
	v_cvt_pk_bf16_f32 v61, v63, v60
	ds_write2_b32 v92, v62, v61 offset0:104 offset1:172
	s_waitcnt lgkmcnt(9)
	v_fma_f32 v62, v7, v63, v117
	v_fma_f32 v61, v6, v63, v116
	v_fma_f32 v61, -v7, v60, v61
	v_fma_f32 v60, v6, v60, v62
	v_cvt_pk_bf16_f32 v62, v61, v60
	s_waitcnt lgkmcnt(8)
	v_fma_f32 v63, -v60, v7, v118
	v_fma_f32 v60, v60, v6, v119
	v_fma_f32 v60, v61, v7, v60
	v_fma_f32 v63, v61, v6, v63
	v_cvt_pk_bf16_f32 v61, v63, v60
	ds_write2_b32 v93, v62, v61 offset0:112 offset1:180
	s_waitcnt lgkmcnt(8)
	v_fma_f32 v62, v7, v63, v121
	v_fma_f32 v61, v6, v63, v120
	v_fma_f32 v61, -v7, v60, v61
	v_fma_f32 v60, v6, v60, v62
	v_cvt_pk_bf16_f32 v62, v61, v60
	s_waitcnt lgkmcnt(7)
	v_fma_f32 v63, v7, v61, v123
	v_fma_f32 v96, v6, v61, v122
	v_fma_f32 v96, -v7, v60, v96
	v_fma_f32 v97, v6, v60, v63
	v_cvt_pk_bf16_f32 v60, v96, v97
	ds_write2_b32 v94, v62, v60 offset0:120 offset1:188
	s_waitcnt lgkmcnt(0)
	ds_read_b128 v[60:63], v0 offset:11520
	ds_read_b128 v[98:101], v0 offset:11584
	s_waitcnt lgkmcnt(1)
	v_mfma_f32_16x16x32_bf16 v[60:63], v[60:63], v[24:27], 0
	ds_read_b128 v[102:105], v0 offset:11648
	v_mov_b32_e32 v65, 0
	v_mov_b32_e32 v66, 0
	s_waitcnt lgkmcnt(1)
	v_mfma_f32_16x16x32_bf16 v[60:63], v[98:101], v[20:23], v[60:63]
	ds_read_b128 v[98:101], v0 offset:11712
	v_mov_b32_e32 v67, 0
	s_waitcnt lgkmcnt(1)
	v_mfma_f32_16x16x32_bf16 v[60:63], v[102:105], v[16:19], v[60:63]
	s_waitcnt lgkmcnt(0)
	v_mfma_f32_16x16x32_bf16 v[60:63], v[98:101], v[12:15], v[60:63]
	s_and_saveexec_b64 s[8:9], vcc
	ds_read_b128 v[64:67], v95 offset:2304
	s_or_b64 exec, exec, s[8:9]
	s_waitcnt lgkmcnt(0)
	v_mfma_f32_16x16x32_bf16 v[52:55], v[64:67], v[52:55], 0
	s_mov_b32 s9, 0x200000
	v_mfma_f32_16x16x32_bf16 v[56:59], v[64:67], v[56:59], 0
	s_nop 7
	ds_write2_b32 v68, v52, v56 offset1:16
	ds_write2_b32 v68, v53, v57 offset0:132 offset1:148
	ds_write2_b32 v69, v54, v58 offset0:8 offset1:24
	ds_write2_b32 v69, v55, v59 offset0:140 offset1:156
	v_mfma_f32_16x16x32_bf16 v[44:47], v[64:67], v[44:47], 0
	v_mfma_f32_16x16x32_bf16 v[48:51], v[64:67], v[48:51], 0
	s_nop 7
	ds_write2_b32 v68, v44, v48 offset0:32 offset1:48
	ds_write2_b32 v68, v45, v49 offset0:164 offset1:180
	ds_write2_b32 v69, v46, v50 offset0:40 offset1:56
	ds_write2_b32 v69, v47, v51 offset0:172 offset1:188
	v_mfma_f32_16x16x32_bf16 v[40:43], v[64:67], v[40:43], 0
	v_mfma_f32_16x16x32_bf16 v[36:39], v[64:67], v[36:39], 0
	s_nop 7
	ds_write2_b32 v68, v40, v36 offset0:64 offset1:80
	ds_write2_b32 v68, v41, v37 offset0:196 offset1:212
	ds_write2_b32 v69, v42, v38 offset0:72 offset1:88
	ds_write2_b32 v69, v43, v39 offset0:204 offset1:220
	v_mfma_f32_16x16x32_bf16 v[32:35], v[64:67], v[32:35], 0
	v_mfma_f32_16x16x32_bf16 v[28:31], v[64:67], v[28:31], 0
	s_nop 7
	ds_write2_b32 v68, v32, v28 offset0:96 offset1:112
	ds_write2_b32 v68, v33, v29 offset0:228 offset1:244
	ds_write2_b32 v69, v34, v30 offset0:104 offset1:120
	ds_write2_b32 v69, v35, v31 offset0:236 offset1:252
	s_waitcnt lgkmcnt(0)
	v_mul_f32_e32 v64, v7, v97
	ds_read2st64_b32 v[28:29], v70 offset0:12 offset1:13
	ds_read2st64_b32 v[30:31], v71 offset0:14 offset1:15
	ds_read2st64_b32 v[32:33], v72 offset0:16 offset1:17
	ds_read2st64_b32 v[34:35], v73 offset0:18 offset1:19
	ds_read2st64_b32 v[36:37], v74 offset0:20 offset1:21
	ds_read2st64_b32 v[38:39], v75 offset0:22 offset1:23
	ds_read2st64_b32 v[40:41], v76 offset0:24 offset1:25
	ds_read2st64_b32 v[42:43], v77 offset0:26 offset1:27
	ds_read2st64_b32 v[44:45], v79 offset0:28 offset1:29
	ds_read2st64_b32 v[46:47], v80 offset0:30 offset1:31
	ds_read2st64_b32 v[48:49], v81 offset0:32 offset1:33
	ds_read2st64_b32 v[50:51], v82 offset0:34 offset1:35
	ds_read2st64_b32 v[52:53], v83 offset0:36 offset1:37
	ds_read2st64_b32 v[54:55], v84 offset0:38 offset1:39
	ds_read2st64_b32 v[56:57], v85 offset0:40 offset1:41
	ds_read2st64_b32 v[58:59], v86 offset0:42 offset1:43
	v_fma_f32 v64, v6, v96, -v64
	s_waitcnt lgkmcnt(14)
	v_add_f32_e32 v28, v64, v28
	v_mul_f32_e32 v64, v7, v96
	v_fmac_f32_e32 v64, v6, v97
	v_add_f32_e32 v29, v64, v29
	v_cvt_pk_bf16_f32 v64, v28, v29
	v_fma_f32 v65, v7, v28, v31
	v_fma_f32 v30, v6, v28, v30
	v_fma_f32 v30, -v7, v29, v30
	v_fma_f32 v28, v6, v29, v65
	v_cvt_pk_bf16_f32 v29, v30, v28
	ds_write2_b32 v87, v64, v29 offset0:64 offset1:132
	s_waitcnt lgkmcnt(14)
	v_fma_f32 v29, -v28, v7, v32
	v_fma_f32 v28, v28, v6, v33
	v_fma_f32 v28, v30, v7, v28
	v_fma_f32 v29, v30, v6, v29
	v_cvt_pk_bf16_f32 v30, v29, v28
	s_waitcnt lgkmcnt(13)
	v_fma_f32 v31, -v28, v7, v34
	v_fma_f32 v28, v28, v6, v35
	v_fma_f32 v28, v29, v7, v28
	v_fma_f32 v31, v29, v6, v31
	v_cvt_pk_bf16_f32 v29, v31, v28
	ds_write2_b32 v88, v30, v29 offset0:72 offset1:140
	s_waitcnt lgkmcnt(13)
	v_fma_f32 v30, v7, v31, v37
	v_fma_f32 v29, v6, v31, v36
	v_fma_f32 v29, -v7, v28, v29
	v_fma_f32 v28, v6, v28, v30
	v_cvt_pk_bf16_f32 v30, v29, v28
	s_waitcnt lgkmcnt(12)
	v_fma_f32 v31, -v28, v7, v38
	v_fma_f32 v28, v28, v6, v39
	v_fma_f32 v28, v29, v7, v28
	v_fma_f32 v31, v29, v6, v31
	v_cvt_pk_bf16_f32 v29, v31, v28
	ds_write2_b32 v89, v30, v29 offset0:80 offset1:148
	s_waitcnt lgkmcnt(12)
	v_fma_f32 v30, v7, v31, v41
	v_fma_f32 v29, v6, v31, v40
	v_fma_f32 v29, -v7, v28, v29
	v_fma_f32 v28, v6, v28, v30
	v_cvt_pk_bf16_f32 v30, v29, v28
	s_waitcnt lgkmcnt(11)
	v_fma_f32 v31, -v28, v7, v42
	v_fma_f32 v28, v28, v6, v43
	v_fma_f32 v28, v29, v7, v28
	v_fma_f32 v31, v29, v6, v31
	v_cvt_pk_bf16_f32 v29, v31, v28
	ds_write2_b32 v90, v30, v29 offset0:88 offset1:156
	s_waitcnt lgkmcnt(11)
	v_fma_f32 v30, v7, v31, v45
	v_fma_f32 v29, v6, v31, v44
	v_fma_f32 v29, -v7, v28, v29
	v_fma_f32 v28, v6, v28, v30
	v_cvt_pk_bf16_f32 v30, v29, v28
	s_waitcnt lgkmcnt(10)
	v_fma_f32 v31, -v28, v7, v46
	v_fma_f32 v28, v28, v6, v47
	v_fma_f32 v28, v29, v7, v28
	v_fma_f32 v31, v29, v6, v31
	v_cvt_pk_bf16_f32 v29, v31, v28
	ds_write2_b32 v91, v30, v29 offset0:96 offset1:164
	s_waitcnt lgkmcnt(10)
	v_fma_f32 v30, v7, v31, v49
	v_fma_f32 v29, v6, v31, v48
	v_fma_f32 v29, -v7, v28, v29
	v_fma_f32 v28, v6, v28, v30
	v_cvt_pk_bf16_f32 v30, v29, v28
	s_waitcnt lgkmcnt(9)
	v_fma_f32 v31, -v28, v7, v50
	v_fma_f32 v28, v28, v6, v51
	v_fma_f32 v28, v29, v7, v28
	v_fma_f32 v31, v29, v6, v31
	v_cvt_pk_bf16_f32 v29, v31, v28
	ds_write2_b32 v92, v30, v29 offset0:104 offset1:172
	s_waitcnt lgkmcnt(9)
	v_fma_f32 v30, v7, v31, v53
	v_fma_f32 v29, v6, v31, v52
	v_fma_f32 v29, -v7, v28, v29
	v_fma_f32 v28, v6, v28, v30
	v_cvt_pk_bf16_f32 v30, v29, v28
	s_waitcnt lgkmcnt(8)
	v_fma_f32 v31, -v28, v7, v54
	v_fma_f32 v28, v28, v6, v55
	v_fma_f32 v28, v29, v7, v28
	v_fma_f32 v31, v29, v6, v31
	v_cvt_pk_bf16_f32 v29, v31, v28
	ds_write2_b32 v93, v30, v29 offset0:112 offset1:180
	s_waitcnt lgkmcnt(8)
	v_fma_f32 v30, v7, v31, v57
	v_fma_f32 v29, v6, v31, v56
	v_fma_f32 v29, -v7, v28, v29
	v_fma_f32 v28, v6, v28, v30
	v_mul_f32_e32 v31, v7, v28
	v_mul_f32_e32 v7, v7, v29
	v_fma_f32 v31, v6, v29, -v31
	v_fmac_f32_e32 v7, v6, v28
	s_waitcnt lgkmcnt(7)
	v_add_f32_e32 v31, v58, v31
	v_add_f32_e32 v6, v59, v7
	v_cvt_pk_bf16_f32 v30, v29, v28
	v_cvt_pk_bf16_f32 v6, v31, v6
	ds_write2_b32 v94, v30, v6 offset0:120 offset1:188
	s_waitcnt lgkmcnt(0)
	ds_read_b128 v[28:31], v0 offset:11520
	s_waitcnt lgkmcnt(0)
	v_mfma_f32_16x16x32_bf16 v[24:27], v[28:31], v[24:27], 0
	ds_read_b128 v[28:31], v0 offset:11584
	v_mov_b32_e32 v73, v204
	v_mov_b32_e32 v72, 0
	s_waitcnt lgkmcnt(0)
	v_mfma_f32_16x16x32_bf16 v[20:23], v[28:31], v[20:23], v[24:27]
	s_nop 2
	ds_read_b128 v[24:27], v0 offset:11648
	v_mov_b32_e32 v75, 0
	v_mov_b32_e32 v76, 0
	s_waitcnt lgkmcnt(0)
	v_mfma_f32_16x16x32_bf16 v[16:19], v[24:27], v[16:19], v[20:23]
	s_nop 2
	ds_read_b128 v[20:23], v0 offset:11712
	v_mov_b32_e32 v0, s59
	ds_read_b64 v[6:7], v0
	v_readfirstlane_b32 s5, v73
	s_lshr_b32 s5, s5, 6
	s_mulk_i32 s5, 0x3e00
	s_add_i32 s8, s5, 0
	v_readlane_b32 s5, v244, 25
	v_and_b32_e32 v59, 63, v73
	s_add_i32 s28, s4, s5
	s_waitcnt lgkmcnt(0)
	v_readfirstlane_b32 s4, v6
	v_lshl_or_b32 v6, s28, 6, v59
	v_readfirstlane_b32 s5, v7
	v_ashrrev_i32_e32 v7, 31, v6
	s_ashr_i32 s29, s28, 31
	v_lshl_add_u64 v[6:7], v[6:7], 4, s[4:5]
	s_lshl_b64 s[38:39], s[28:29], 13
	v_add_co_u32_e32 v6, vcc, s9, v6
	s_add_u32 s38, s4, s38
	v_and_b32_e32 v58, 15, v73
	v_addc_co_u32_e32 v7, vcc, 0, v7, vcc
	s_addc_u32 s39, s5, s39
	v_and_b32_e32 v0, 48, v73
	v_mfma_f32_16x16x32_bf16 v[12:15], v[20:23], v[12:15], v[16:19]
	global_load_dwordx2 v[32:33], v[6:7], off
	v_lshl_add_u64 v[6:7], s[38:39], 0, v[0:1]
	s_mov_b32 s9, 0x240000
	v_lshlrev_b32_e32 v16, 6, v58
	v_mov_b32_e32 v17, v1
	v_lshl_add_u64 v[6:7], v[6:7], 0, v[16:17]
	v_add_co_u32_e32 v18, vcc, s9, v6
	s_mov_b64 s[38:39], 0x240000
	s_nop 0
	v_addc_co_u32_e32 v19, vcc, 0, v7, vcc
	s_mov_b32 s9, 0x241000
	v_lshl_add_u64 v[16:17], v[6:7], 0, s[38:39]
	v_add_co_u32_e32 v6, vcc, s9, v6
	s_lshl_b64 s[28:29], s[28:29], 12
	s_nop 0
	v_addc_co_u32_e32 v7, vcc, 0, v7, vcc
	s_add_u32 s28, s4, s28
	global_load_dwordx4 v[42:45], v[18:19], off
	global_load_dwordx4 v[68:71], v[16:17], off offset:1024
	global_load_dwordx4 v[64:67], v[16:17], off offset:2048
	global_load_dwordx4 v[50:53], v[16:17], off offset:3072
	global_load_dwordx4 v[54:57], v[6:7], off
	global_load_dwordx4 v[46:49], v[6:7], off offset:1024
	global_load_dwordx4 v[38:41], v[6:7], off offset:2048
	s_waitcnt lgkmcnt(0)
	global_load_dwordx4 v[34:37], v[6:7], off offset:3072
	s_addc_u32 s29, s5, s29
	v_lshlrev_b32_e32 v6, 8, v58
	v_mov_b32_e32 v7, v1
	v_lshl_add_u64 v[6:7], s[28:29], 0, v[6:7]
	v_lshl_add_u64 v[6:7], v[6:7], 0, v[0:1]
	s_mov_b64 s[28:29], 0x380000
	s_mov_b32 s9, 0x380000
	v_lshl_add_u64 v[16:17], v[6:7], 0, s[28:29]
	v_add_co_u32_e32 v6, vcc, s9, v6
	s_or_b32 s9, s26, 1
	s_mul_hi_i32 s28, s9, 0x44
	s_mulk_i32 s9, 0x44
	s_add_u32 s26, s9, s22
	s_addc_u32 s27, s28, s27
	s_lshl_b64 s[26:27], s[26:27], 10
	s_add_u32 s6, s26, s6
	v_addc_co_u32_e32 v7, vcc, 0, v7, vcc
	s_addc_u32 s7, s27, s7
	global_load_dwordx4 v[20:23], v[6:7], off
	global_load_dwordx4 v[28:31], v[16:17], off offset:64
	global_load_dwordx4 v[24:27], v[16:17], off offset:128
	s_nop 0
	global_load_dwordx4 v[16:19], v[16:17], off offset:192
	v_or_b32_e32 v6, s6, v59
	v_mov_b32_e32 v7, s7
	v_lshl_add_u64 v[6:7], v[6:7], 3, s[4:5]
	v_add_co_u32_e32 v6, vcc, 0x1500000, v6
	v_add_u32_e32 v74, s8, v0
	s_nop 0
	v_addc_co_u32_e32 v7, vcc, 0, v7, vcc
	global_load_dwordx2 v[6:7], v[6:7], off
	v_cmp_gt_u32_e32 vcc, 32, v59
	v_mad_u32_u24 v81, v58, 48, v74
	v_mov_b32_e32 v74, 0
	v_mov_b32_e32 v77, 0
	s_and_saveexec_b64 s[4:5], vcc
	ds_read_b128 v[74:77], v81 offset:2304
	s_or_b64 exec, exec, s[4:5]
	s_waitcnt vmcnt(6) lgkmcnt(0)
	v_mfma_f32_16x16x32_bf16 v[82:85], v[74:77], v[42:45], 0
	v_bfe_u32 v73, v73, 4, 2
	v_mov_b32_e32 v80, s8
	s_movk_i32 s4, 0x110
	v_mfma_f32_16x16x32_bf16 v[86:89], v[74:77], v[68:71], 0
	v_lshlrev_b32_e32 v79, 2, v58
	v_mad_u32_u24 v126, v58, s4, v80
	v_mul_u32_u24_e32 v58, 0x840, v73
	v_mfma_f32_16x16x32_bf16 v[90:93], v[74:77], v[64:67], 0
	v_add3_u32 v58, s8, v79, v58
	v_add_u32_e32 v80, 0xc00, v58
	s_nop 1
	ds_write2_b32 v80, v82, v86 offset1:16
	v_mfma_f32_16x16x32_bf16 v[94:97], v[74:77], v[50:53], 0
	v_add_u32_e32 v82, 0x1000, v58
	ds_write2_b32 v80, v83, v87 offset0:132 offset1:148
	ds_write2_b32 v82, v84, v88 offset0:8 offset1:24
	v_mfma_f32_16x16x32_bf16 v[98:101], v[74:77], v[54:57], 0
	ds_write2_b32 v82, v85, v89 offset0:140 offset1:156
	s_nop 2
	ds_write2_b32 v80, v90, v94 offset0:32 offset1:48
	ds_write2_b32 v80, v91, v95 offset0:164 offset1:180
	v_lshlrev_b32_e32 v59, 2, v59
	v_add_u32_e32 v83, s8, v59
	v_mfma_f32_16x16x32_bf16 v[84:87], v[74:77], v[46:49], 0
	ds_write2_b32 v82, v92, v96 offset0:40 offset1:56
	ds_write2_b32 v82, v93, v97 offset0:172 offset1:188
	s_nop 5
	ds_write2_b32 v80, v98, v84 offset0:64 offset1:80
	ds_write2_b32 v80, v99, v85 offset0:196 offset1:212
	ds_write2_b32 v82, v100, v86 offset0:72 offset1:88
	ds_write2_b32 v82, v101, v87 offset0:204 offset1:220
	v_mfma_f32_16x16x32_bf16 v[88:91], v[74:77], v[38:41], 0
	v_add_u32_e32 v84, 0xf0, v83
	v_add_u32_e32 v85, 0xe0, v83
	s_waitcnt vmcnt(0)
	v_mul_f32_e32 v73, v33, v7
	v_mfma_f32_16x16x32_bf16 v[74:77], v[74:77], v[34:37], 0
	s_nop 7
	ds_write2_b32 v80, v88, v74 offset0:96 offset1:112
	ds_write2_b32 v80, v89, v75 offset0:228 offset1:244
	ds_write2_b32 v82, v90, v76 offset0:104 offset1:120
	ds_write2_b32 v82, v91, v77 offset0:236 offset1:252
	s_waitcnt lgkmcnt(0)
	ds_read2st64_b32 v[58:59], v84 offset0:42 offset1:43
	ds_read2st64_b32 v[74:75], v85 offset0:40 offset1:41
	v_fma_f32 v73, v32, v6, -v73
	v_mul_f32_e32 v6, v33, v6
	v_fmac_f32_e32 v6, v32, v7
	s_waitcnt lgkmcnt(1)
	v_add_f32_e32 v58, v73, v58
	v_add_f32_e32 v6, v6, v59
	v_add_u32_e32 v86, 0xd0, v83
	v_cvt_pk_bf16_f32 v7, v58, v6
	ds_read2st64_b32 v[76:77], v86 offset0:38 offset1:39
	s_waitcnt lgkmcnt(1)
	v_fma_f32 v59, -v6, v33, v74
	v_fma_f32 v6, v6, v32, v75
	v_fma_f32 v6, v58, v33, v6
	v_fma_f32 v59, v58, v32, v59
	v_add_u32_e32 v87, 0xc0, v83
	v_add_u32_e32 v88, 0xb0, v83
	v_add_u32_e32 v89, 0xa0, v83
	v_add_u32_e32 v90, 0x90, v83
	v_add_u32_e32 v91, 0x80, v83
	v_add_u32_e32 v92, 0x70, v83
	v_add_u32_e32 v93, 0x60, v83
	v_add_u32_e32 v94, 0x50, v83
	v_add_u32_e32 v95, 64, v83
	v_add_u32_e32 v96, 48, v83
	v_add_u32_e32 v97, 32, v83
	v_add_u32_e32 v98, 16, v83
	v_cvt_pk_bf16_f32 v58, v59, v6
	v_add_u32_e32 v99, 0x3a00, v83
	ds_read2st64_b32 v[100:101], v87 offset0:36 offset1:37
	ds_read2st64_b32 v[102:103], v88 offset0:34 offset1:35
	ds_read2st64_b32 v[104:105], v89 offset0:32 offset1:33
	ds_read2st64_b32 v[106:107], v90 offset0:30 offset1:31
	ds_read2st64_b32 v[108:109], v91 offset0:28 offset1:29
	ds_read2st64_b32 v[110:111], v92 offset0:26 offset1:27
	ds_read2st64_b32 v[112:113], v93 offset0:24 offset1:25
	ds_read2st64_b32 v[114:115], v94 offset0:22 offset1:23
	ds_read2st64_b32 v[116:117], v95 offset0:20 offset1:21
	ds_read2st64_b32 v[118:119], v96 offset0:18 offset1:19
	ds_read2st64_b32 v[120:121], v97 offset0:16 offset1:17
	ds_read2st64_b32 v[122:123], v98 offset0:14 offset1:15
	ds_read2st64_b32 v[124:125], v83 offset0:12 offset1:13
	ds_write2_b32 v99, v58, v7 offset0:120 offset1:188
	s_waitcnt lgkmcnt(14)
	v_fma_f32 v58, v33, v59, v77
	v_fma_f32 v7, v32, v59, v76
	v_fma_f32 v7, -v33, v6, v7
	v_fma_f32 v6, v32, v6, v58
	v_cvt_pk_bf16_f32 v58, v7, v6
	s_waitcnt lgkmcnt(13)
	v_fma_f32 v59, -v6, v33, v100
	v_fma_f32 v6, v6, v32, v101
	v_fma_f32 v6, v7, v33, v6
	v_fma_f32 v59, v7, v32, v59
	v_cvt_pk_bf16_f32 v7, v59, v6
	v_add_u32_e32 v100, 0x3800, v83
	ds_write2_b32 v100, v7, v58 offset0:112 offset1:180
	s_waitcnt lgkmcnt(13)
	v_fma_f32 v58, v33, v59, v103
	v_fma_f32 v7, v32, v59, v102
	v_fma_f32 v7, -v33, v6, v7
	v_fma_f32 v6, v32, v6, v58
	v_cvt_pk_bf16_f32 v58, v7, v6
	s_waitcnt lgkmcnt(12)
	v_fma_f32 v59, -v6, v33, v104
	v_fma_f32 v6, v6, v32, v105
	v_fma_f32 v6, v7, v33, v6
	v_fma_f32 v59, v7, v32, v59
	v_cvt_pk_bf16_f32 v7, v59, v6
	v_add_u32_e32 v101, 0x3600, v83
	ds_write2_b32 v101, v7, v58 offset0:104 offset1:172
	s_waitcnt lgkmcnt(12)
	v_fma_f32 v58, v33, v59, v107
	v_fma_f32 v7, v32, v59, v106
	v_fma_f32 v7, -v33, v6, v7
	v_fma_f32 v6, v32, v6, v58
	v_cvt_pk_bf16_f32 v58, v7, v6
	s_waitcnt lgkmcnt(11)
	v_fma_f32 v59, -v6, v33, v108
	v_fma_f32 v6, v6, v32, v109
	v_fma_f32 v6, v7, v33, v6
	v_fma_f32 v59, v7, v32, v59
	v_cvt_pk_bf16_f32 v7, v59, v6
	v_add_u32_e32 v102, 0x3400, v83
	ds_write2_b32 v102, v7, v58 offset0:96 offset1:164
	s_waitcnt lgkmcnt(11)
	v_fma_f32 v58, v33, v59, v111
	v_fma_f32 v7, v32, v59, v110
	v_fma_f32 v7, -v33, v6, v7
	v_fma_f32 v6, v32, v6, v58
	v_cvt_pk_bf16_f32 v58, v7, v6
	s_waitcnt lgkmcnt(10)
	v_fma_f32 v59, -v6, v33, v112
	v_fma_f32 v6, v6, v32, v113
	v_fma_f32 v6, v7, v33, v6
	v_fma_f32 v59, v7, v32, v59
	v_cvt_pk_bf16_f32 v7, v59, v6
	v_add_u32_e32 v103, 0x3200, v83
	ds_write2_b32 v103, v7, v58 offset0:88 offset1:156
	s_waitcnt lgkmcnt(10)
	v_fma_f32 v58, v33, v59, v115
	v_fma_f32 v7, v32, v59, v114
	v_fma_f32 v7, -v33, v6, v7
	v_fma_f32 v6, v32, v6, v58
	v_cvt_pk_bf16_f32 v58, v7, v6
	s_waitcnt lgkmcnt(9)
	v_fma_f32 v59, -v6, v33, v116
	v_fma_f32 v6, v6, v32, v117
	v_fma_f32 v6, v7, v33, v6
	v_fma_f32 v59, v7, v32, v59
	v_cvt_pk_bf16_f32 v7, v59, v6
	v_add_u32_e32 v104, 0x3000, v83
	ds_write2_b32 v104, v7, v58 offset0:80 offset1:148
	s_waitcnt lgkmcnt(9)
	v_fma_f32 v58, v33, v59, v119
	v_fma_f32 v7, v32, v59, v118
	v_fma_f32 v7, -v33, v6, v7
	v_fma_f32 v6, v32, v6, v58
	v_cvt_pk_bf16_f32 v58, v7, v6
	s_waitcnt lgkmcnt(8)
	v_fma_f32 v59, -v6, v33, v120
	v_fma_f32 v6, v6, v32, v121
	v_fma_f32 v6, v7, v33, v6
	v_fma_f32 v59, v7, v32, v59
	v_cvt_pk_bf16_f32 v7, v59, v6
	v_add_u32_e32 v105, 0x2e00, v83
	ds_write2_b32 v105, v7, v58 offset0:72 offset1:140
	s_waitcnt lgkmcnt(8)
	v_fma_f32 v58, v33, v59, v123
	v_fma_f32 v7, v32, v59, v122
	v_fma_f32 v7, -v33, v6, v7
	v_fma_f32 v58, v32, v6, v58
	v_mul_f32_e32 v6, v33, v58
	v_cvt_pk_bf16_f32 v59, v7, v58
	v_fma_f32 v6, v32, v7, -v6
	v_mul_f32_e32 v7, v33, v7
	v_fmac_f32_e32 v7, v32, v58
	s_waitcnt lgkmcnt(7)
	v_add_f32_e32 v6, v124, v6
	v_add_f32_e32 v7, v125, v7
	v_cvt_pk_bf16_f32 v58, v6, v7
	v_add_u32_e32 v106, 0x2c00, v83
	ds_write2_b32 v106, v58, v59 offset0:64 offset1:132
	s_waitcnt lgkmcnt(0)
	v_add_u32_e32 v79, v126, v0
	ds_read_b128 v[74:77], v79 offset:11520
	ds_read_b128 v[108:111], v79 offset:11584
	s_waitcnt lgkmcnt(1)
	v_mfma_f32_16x16x32_bf16 v[12:15], v[74:77], v[20:23], v[12:15]
	ds_read_b128 v[74:77], v79 offset:11648
	v_mov_b32_e32 v73, 0
	s_waitcnt lgkmcnt(1)
	v_mfma_f32_16x16x32_bf16 v[12:15], v[108:111], v[28:31], v[12:15]
	ds_read_b128 v[108:111], v79 offset:11712
	s_waitcnt lgkmcnt(1)
	v_mfma_f32_16x16x32_bf16 v[12:15], v[74:77], v[24:27], v[12:15]
	v_mov_b32_e32 v74, 0
	v_mov_b32_e32 v75, 0
	s_waitcnt lgkmcnt(0)
	v_mfma_f32_16x16x32_bf16 v[12:15], v[108:111], v[16:19], v[12:15]
	s_and_saveexec_b64 s[4:5], vcc
	ds_read_b128 v[72:75], v81 offset:1536
	s_or_b64 exec, exec, s[4:5]
	s_waitcnt lgkmcnt(0)
	v_mfma_f32_16x16x32_bf16 v[108:111], v[72:75], v[42:45], 0
	v_mul_f32_e32 v0, v33, v7
	v_fma_f32 v0, v32, v6, -v0
	v_mul_f32_e32 v6, v33, v6
	v_mfma_f32_16x16x32_bf16 v[112:115], v[72:75], v[68:71], 0
	s_nop 7
	ds_write2_b32 v80, v108, v112 offset1:16
	ds_write2_b32 v80, v109, v113 offset0:132 offset1:148
	ds_write2_b32 v82, v110, v114 offset0:8 offset1:24
	v_mfma_f32_16x16x32_bf16 v[116:119], v[72:75], v[64:67], 0
	v_fmac_f32_e32 v6, v32, v7
	v_mfma_f32_16x16x32_bf16 v[120:123], v[72:75], v[50:53], 0
	ds_write2_b32 v82, v111, v115 offset0:140 offset1:156
	s_nop 6
	ds_write2_b32 v80, v116, v120 offset0:32 offset1:48
	ds_write2_b32 v80, v117, v121 offset0:164 offset1:180
	v_mfma_f32_16x16x32_bf16 v[124:127], v[72:75], v[54:57], 0
	v_mfma_f32_16x16x32_bf16 v[108:111], v[72:75], v[46:49], 0
	ds_write2_b32 v82, v118, v122 offset0:40 offset1:56
	ds_write2_b32 v82, v119, v123 offset0:172 offset1:188
	s_nop 5
	ds_write2_b32 v80, v124, v108 offset0:64 offset1:80
	ds_write2_b32 v80, v125, v109 offset0:196 offset1:212
	ds_write2_b32 v82, v126, v110 offset0:72 offset1:88
	ds_write2_b32 v82, v127, v111 offset0:204 offset1:220
	v_mfma_f32_16x16x32_bf16 v[112:115], v[72:75], v[38:41], 0
	v_mfma_f32_16x16x32_bf16 v[72:75], v[72:75], v[34:37], 0
	s_nop 7
	ds_write2_b32 v80, v112, v72 offset0:96 offset1:112
	ds_write2_b32 v80, v113, v73 offset0:228 offset1:244
	ds_write2_b32 v82, v114, v74 offset0:104 offset1:120
	ds_write2_b32 v82, v115, v75 offset0:236 offset1:252
	s_waitcnt lgkmcnt(0)
	ds_read2st64_b32 v[58:59], v84 offset0:42 offset1:43
	ds_read2st64_b32 v[72:73], v85 offset0:40 offset1:41
	ds_read2st64_b32 v[74:75], v86 offset0:38 offset1:39
	ds_read2st64_b32 v[76:77], v87 offset0:36 offset1:37
	ds_read2st64_b32 v[108:109], v88 offset0:34 offset1:35
	ds_read2st64_b32 v[110:111], v89 offset0:32 offset1:33
	ds_read2st64_b32 v[112:113], v90 offset0:30 offset1:31
	ds_read2st64_b32 v[114:115], v91 offset0:28 offset1:29
	ds_read2st64_b32 v[116:117], v92 offset0:26 offset1:27
	ds_read2st64_b32 v[118:119], v93 offset0:24 offset1:25
	ds_read2st64_b32 v[120:121], v94 offset0:22 offset1:23
	ds_read2st64_b32 v[122:123], v95 offset0:20 offset1:21
	ds_read2st64_b32 v[124:125], v96 offset0:18 offset1:19
	ds_read2st64_b32 v[126:127], v97 offset0:16 offset1:17
	ds_read2st64_b32 v[128:129], v98 offset0:14 offset1:15
	ds_read2st64_b32 v[130:131], v83 offset0:12 offset1:13
	s_waitcnt lgkmcnt(14)
	v_add_f32_e32 v0, v0, v58
	v_add_f32_e32 v6, v6, v59
	v_cvt_pk_bf16_f32 v7, v0, v6
	v_mul_f32_e32 v58, v33, v6
	v_mul_f32_e32 v6, v32, v6
	v_fma_f32 v58, v32, v0, -v58
	v_fmac_f32_e32 v6, v33, v0
	v_add_f32_e32 v58, v72, v58
	v_add_f32_e32 v0, v73, v6
	v_cvt_pk_bf16_f32 v6, v58, v0
	ds_write2_b32 v99, v6, v7 offset0:120 offset1:188
	s_waitcnt lgkmcnt(14)
	v_fma_f32 v7, v33, v58, v75
	v_fma_f32 v6, v32, v58, v74
	v_fma_f32 v6, -v33, v0, v6
	v_fma_f32 v0, v32, v0, v7
	v_cvt_pk_bf16_f32 v7, v6, v0
	s_waitcnt lgkmcnt(13)
	v_fma_f32 v58, -v0, v33, v76
	v_fma_f32 v0, v0, v32, v77
	v_fma_f32 v0, v6, v33, v0
	v_fma_f32 v58, v6, v32, v58
	v_cvt_pk_bf16_f32 v6, v58, v0
	ds_write2_b32 v100, v6, v7 offset0:112 offset1:180
	s_waitcnt lgkmcnt(13)
	v_fma_f32 v7, v33, v58, v109
	v_fma_f32 v6, v32, v58, v108
	v_fma_f32 v6, -v33, v0, v6
	v_fma_f32 v0, v32, v0, v7
	v_cvt_pk_bf16_f32 v7, v6, v0
	s_waitcnt lgkmcnt(12)
	v_fma_f32 v58, -v0, v33, v110
	v_fma_f32 v0, v0, v32, v111
	v_fma_f32 v0, v6, v33, v0
	v_fma_f32 v58, v6, v32, v58
	v_cvt_pk_bf16_f32 v6, v58, v0
	ds_write2_b32 v101, v6, v7 offset0:104 offset1:172
	s_waitcnt lgkmcnt(12)
	v_fma_f32 v7, v33, v58, v113
	v_fma_f32 v6, v32, v58, v112
	v_fma_f32 v6, -v33, v0, v6
	v_fma_f32 v0, v32, v0, v7
	v_cvt_pk_bf16_f32 v7, v6, v0
	s_waitcnt lgkmcnt(11)
	v_fma_f32 v58, -v0, v33, v114
	v_fma_f32 v0, v0, v32, v115
	v_fma_f32 v0, v6, v33, v0
	v_fma_f32 v58, v6, v32, v58
	v_cvt_pk_bf16_f32 v6, v58, v0
	ds_write2_b32 v102, v6, v7 offset0:96 offset1:164
	s_waitcnt lgkmcnt(11)
	v_fma_f32 v7, v33, v58, v117
	v_fma_f32 v6, v32, v58, v116
	v_fma_f32 v6, -v33, v0, v6
	v_fma_f32 v0, v32, v0, v7
	v_cvt_pk_bf16_f32 v7, v6, v0
	s_waitcnt lgkmcnt(10)
	v_fma_f32 v58, -v0, v33, v118
	v_fma_f32 v0, v0, v32, v119
	v_fma_f32 v0, v6, v33, v0
	v_fma_f32 v58, v6, v32, v58
	v_cvt_pk_bf16_f32 v6, v58, v0
	ds_write2_b32 v103, v6, v7 offset0:88 offset1:156
	s_waitcnt lgkmcnt(10)
	v_fma_f32 v7, v33, v58, v121
	v_fma_f32 v6, v32, v58, v120
	v_fma_f32 v6, -v33, v0, v6
	v_fma_f32 v0, v32, v0, v7
	v_cvt_pk_bf16_f32 v7, v6, v0
	s_waitcnt lgkmcnt(9)
	v_fma_f32 v58, -v0, v33, v122
	v_fma_f32 v0, v0, v32, v123
	v_fma_f32 v0, v6, v33, v0
	v_fma_f32 v58, v6, v32, v58
	v_cvt_pk_bf16_f32 v6, v58, v0
	ds_write2_b32 v104, v6, v7 offset0:80 offset1:148
	s_waitcnt lgkmcnt(9)
	v_fma_f32 v7, v33, v58, v125
	v_fma_f32 v6, v32, v58, v124
	v_fma_f32 v6, -v33, v0, v6
	v_fma_f32 v0, v32, v0, v7
	v_cvt_pk_bf16_f32 v7, v6, v0
	s_waitcnt lgkmcnt(8)
	v_fma_f32 v58, -v0, v33, v126
	v_fma_f32 v0, v0, v32, v127
	v_fma_f32 v0, v6, v33, v0
	v_fma_f32 v58, v6, v32, v58
	v_cvt_pk_bf16_f32 v6, v58, v0
	ds_write2_b32 v105, v6, v7 offset0:72 offset1:140
	s_waitcnt lgkmcnt(8)
	v_fma_f32 v7, v33, v58, v129
	v_fma_f32 v6, v32, v58, v128
	v_fma_f32 v6, -v33, v0, v6
	v_fma_f32 v7, v32, v0, v7
	v_mul_f32_e32 v0, v33, v7
	v_cvt_pk_bf16_f32 v58, v6, v7
	v_fma_f32 v0, v32, v6, -v0
	v_mul_f32_e32 v6, v33, v6
	v_fmac_f32_e32 v6, v32, v7
	s_waitcnt lgkmcnt(7)
	v_add_f32_e32 v0, v130, v0
	v_add_f32_e32 v6, v131, v6
	v_cvt_pk_bf16_f32 v7, v0, v6
	ds_write2_b32 v106, v7, v58 offset0:64 offset1:132
	s_waitcnt lgkmcnt(0)
	ds_read_b128 v[72:75], v79 offset:11520
	ds_read_b128 v[108:111], v79 offset:11584
	s_waitcnt lgkmcnt(1)
	v_mfma_f32_16x16x32_bf16 v[58:61], v[72:75], v[20:23], v[60:63]
	ds_read_b128 v[72:75], v79 offset:11648
	v_mov_b32_e32 v76, 0
	v_mov_b32_e32 v77, 0
	s_waitcnt lgkmcnt(1)
	v_mfma_f32_16x16x32_bf16 v[58:61], v[108:111], v[28:31], v[58:61]
	ds_read_b128 v[108:111], v79 offset:11712
	s_waitcnt lgkmcnt(1)
	v_mfma_f32_16x16x32_bf16 v[58:61], v[72:75], v[24:27], v[58:61]
	v_mov_b32_e32 v72, 0
	v_mov_b32_e32 v74, 0
	v_mov_b32_e32 v75, 0
	s_waitcnt lgkmcnt(0)
	v_mfma_f32_16x16x32_bf16 v[58:61], v[108:111], v[16:19], v[58:61]
	s_and_saveexec_b64 s[4:5], vcc
	ds_read_b128 v[74:77], v81 offset:768
	s_or_b64 exec, exec, s[4:5]
	s_waitcnt lgkmcnt(0)
	v_mfma_f32_16x16x32_bf16 v[108:111], v[74:77], v[42:45], 0
	v_mul_f32_e32 v7, v33, v6
	v_fma_f32 v7, v32, v0, -v7
	v_mul_f32_e32 v0, v33, v0
	v_mfma_f32_16x16x32_bf16 v[112:115], v[74:77], v[68:71], 0
	s_nop 7
	ds_write2_b32 v80, v108, v112 offset1:16
	ds_write2_b32 v80, v109, v113 offset0:132 offset1:148
	ds_write2_b32 v82, v110, v114 offset0:8 offset1:24
	v_mfma_f32_16x16x32_bf16 v[116:119], v[74:77], v[64:67], 0
	v_fmac_f32_e32 v0, v32, v6
	v_mov_b32_e32 v73, 0
	v_mfma_f32_16x16x32_bf16 v[120:123], v[74:77], v[50:53], 0
	ds_write2_b32 v82, v111, v115 offset0:140 offset1:156
	s_nop 6
	ds_write2_b32 v80, v116, v120 offset0:32 offset1:48
	ds_write2_b32 v80, v117, v121 offset0:164 offset1:180
	v_mfma_f32_16x16x32_bf16 v[124:127], v[74:77], v[54:57], 0
	v_mfma_f32_16x16x32_bf16 v[108:111], v[74:77], v[46:49], 0
	ds_write2_b32 v82, v118, v122 offset0:40 offset1:56
	ds_write2_b32 v82, v119, v123 offset0:172 offset1:188
	s_nop 5
	ds_write2_b32 v80, v124, v108 offset0:64 offset1:80
	ds_write2_b32 v80, v125, v109 offset0:196 offset1:212
	ds_write2_b32 v82, v126, v110 offset0:72 offset1:88
	ds_write2_b32 v82, v127, v111 offset0:204 offset1:220
	v_mfma_f32_16x16x32_bf16 v[112:115], v[74:77], v[38:41], 0
	v_mfma_f32_16x16x32_bf16 v[74:77], v[74:77], v[34:37], 0
	s_nop 7
	ds_write2_b32 v80, v112, v74 offset0:96 offset1:112
	ds_write2_b32 v80, v113, v75 offset0:228 offset1:244
	ds_write2_b32 v82, v114, v76 offset0:104 offset1:120
	ds_write2_b32 v82, v115, v77 offset0:236 offset1:252
	s_waitcnt lgkmcnt(0)
	ds_read2st64_b32 v[62:63], v84 offset0:42 offset1:43
	ds_read2st64_b32 v[74:75], v85 offset0:40 offset1:41
	ds_read2st64_b32 v[76:77], v86 offset0:38 offset1:39
	ds_read2st64_b32 v[108:109], v87 offset0:36 offset1:37
	ds_read2st64_b32 v[110:111], v88 offset0:34 offset1:35
	ds_read2st64_b32 v[112:113], v89 offset0:32 offset1:33
	ds_read2st64_b32 v[114:115], v90 offset0:30 offset1:31
	ds_read2st64_b32 v[116:117], v91 offset0:28 offset1:29
	ds_read2st64_b32 v[118:119], v92 offset0:26 offset1:27
	ds_read2st64_b32 v[120:121], v93 offset0:24 offset1:25
	ds_read2st64_b32 v[122:123], v94 offset0:22 offset1:23
	ds_read2st64_b32 v[124:125], v95 offset0:20 offset1:21
	ds_read2st64_b32 v[126:127], v96 offset0:18 offset1:19
	ds_read2st64_b32 v[128:129], v97 offset0:16 offset1:17
	ds_read2st64_b32 v[130:131], v98 offset0:14 offset1:15
	ds_read2st64_b32 v[132:133], v83 offset0:12 offset1:13
	s_waitcnt lgkmcnt(14)
	v_add_f32_e32 v7, v7, v62
	v_add_f32_e32 v0, v0, v63
	v_cvt_pk_bf16_f32 v6, v7, v0
	v_fma_f32 v62, -v0, v33, v74
	v_fma_f32 v0, v0, v32, v75
	v_fma_f32 v0, v7, v33, v0
	v_fma_f32 v62, v7, v32, v62
	v_cvt_pk_bf16_f32 v7, v62, v0
	ds_write2_b32 v99, v7, v6 offset0:120 offset1:188
	s_waitcnt lgkmcnt(14)
	v_fma_f32 v7, v33, v62, v77
	v_fma_f32 v6, v32, v62, v76
	v_fma_f32 v6, -v33, v0, v6
	v_fma_f32 v0, v32, v0, v7
	v_cvt_pk_bf16_f32 v7, v6, v0
	s_waitcnt lgkmcnt(13)
	v_fma_f32 v62, -v0, v33, v108
	v_fma_f32 v0, v0, v32, v109
	v_fma_f32 v0, v6, v33, v0
	v_fma_f32 v62, v6, v32, v62
	v_cvt_pk_bf16_f32 v6, v62, v0
	ds_write2_b32 v100, v6, v7 offset0:112 offset1:180
	s_waitcnt lgkmcnt(13)
	v_fma_f32 v7, v33, v62, v111
	v_fma_f32 v6, v32, v62, v110
	v_fma_f32 v6, -v33, v0, v6
	v_fma_f32 v0, v32, v0, v7
	v_cvt_pk_bf16_f32 v7, v6, v0
	s_waitcnt lgkmcnt(12)
	v_fma_f32 v62, -v0, v33, v112
	v_fma_f32 v0, v0, v32, v113
	v_fma_f32 v0, v6, v33, v0
	v_fma_f32 v62, v6, v32, v62
	v_cvt_pk_bf16_f32 v6, v62, v0
	ds_write2_b32 v101, v6, v7 offset0:104 offset1:172
	s_waitcnt lgkmcnt(12)
	v_fma_f32 v7, v33, v62, v115
	v_fma_f32 v6, v32, v62, v114
	v_fma_f32 v6, -v33, v0, v6
	v_fma_f32 v0, v32, v0, v7
	v_cvt_pk_bf16_f32 v7, v6, v0
	s_waitcnt lgkmcnt(11)
	v_fma_f32 v62, -v0, v33, v116
	v_fma_f32 v0, v0, v32, v117
	v_fma_f32 v0, v6, v33, v0
	v_fma_f32 v62, v6, v32, v62
	v_cvt_pk_bf16_f32 v6, v62, v0
	ds_write2_b32 v102, v6, v7 offset0:96 offset1:164
	s_waitcnt lgkmcnt(11)
	v_fma_f32 v7, v33, v62, v119
	v_fma_f32 v6, v32, v62, v118
	v_fma_f32 v6, -v33, v0, v6
	v_fma_f32 v0, v32, v0, v7
	v_cvt_pk_bf16_f32 v7, v6, v0
	s_waitcnt lgkmcnt(10)
	v_fma_f32 v62, -v0, v33, v120
	v_fma_f32 v0, v0, v32, v121
	v_fma_f32 v0, v6, v33, v0
	v_fma_f32 v62, v6, v32, v62
	v_cvt_pk_bf16_f32 v6, v62, v0
	ds_write2_b32 v103, v6, v7 offset0:88 offset1:156
	s_waitcnt lgkmcnt(10)
	v_fma_f32 v7, v33, v62, v123
	v_fma_f32 v6, v32, v62, v122
	v_fma_f32 v6, -v33, v0, v6
	v_fma_f32 v0, v32, v0, v7
	v_cvt_pk_bf16_f32 v7, v6, v0
	s_waitcnt lgkmcnt(9)
	v_fma_f32 v62, -v0, v33, v124
	v_fma_f32 v0, v0, v32, v125
	v_fma_f32 v0, v6, v33, v0
	v_fma_f32 v62, v6, v32, v62
	v_cvt_pk_bf16_f32 v6, v62, v0
	ds_write2_b32 v104, v6, v7 offset0:80 offset1:148
	s_waitcnt lgkmcnt(9)
	v_fma_f32 v7, v33, v62, v127
	v_fma_f32 v6, v32, v62, v126
	v_fma_f32 v6, -v33, v0, v6
	v_fma_f32 v0, v32, v0, v7
	v_cvt_pk_bf16_f32 v7, v6, v0
	s_waitcnt lgkmcnt(8)
	v_fma_f32 v62, -v0, v33, v128
	v_fma_f32 v0, v0, v32, v129
	v_fma_f32 v0, v6, v33, v0
	v_fma_f32 v62, v6, v32, v62
	v_cvt_pk_bf16_f32 v6, v62, v0
	ds_write2_b32 v105, v6, v7 offset0:72 offset1:140
	s_waitcnt lgkmcnt(8)
	v_fma_f32 v7, v33, v62, v131
	v_fma_f32 v6, v32, v62, v130
	v_fma_f32 v6, -v33, v0, v6
	v_fma_f32 v7, v32, v0, v7
	v_cvt_pk_bf16_f32 v63, v6, v7
	s_waitcnt lgkmcnt(7)
	v_fma_f32 v0, -v33, v7, v132
	v_fma_f32 v62, v33, v6, v133
	v_fma_f32 v62, v32, v7, v62
	v_fma_f32 v0, v32, v6, v0
	v_cvt_pk_bf16_f32 v6, v0, v62
	ds_write2_b32 v106, v6, v63 offset0:64 offset1:132
	s_waitcnt lgkmcnt(0)
	ds_read_b128 v[74:77], v79 offset:11520
	ds_read_b128 v[108:111], v79 offset:11584
	s_waitcnt lgkmcnt(1)
	v_mfma_f32_16x16x32_bf16 v[6:9], v[74:77], v[20:23], v[8:11]
	ds_read_b128 v[74:77], v79 offset:11648
	s_waitcnt lgkmcnt(1)
	v_mfma_f32_16x16x32_bf16 v[6:9], v[108:111], v[28:31], v[6:9]
	ds_read_b128 v[108:111], v79 offset:11712
	s_waitcnt lgkmcnt(1)
	v_mfma_f32_16x16x32_bf16 v[6:9], v[74:77], v[24:27], v[6:9]
	v_mov_b32_e32 v74, 0
	v_mov_b32_e32 v75, 0
	s_waitcnt lgkmcnt(0)
	v_mfma_f32_16x16x32_bf16 v[6:9], v[108:111], v[16:19], v[6:9]
	s_and_saveexec_b64 s[4:5], vcc
	s_cbranch_execz .LBB0_275
	ds_read_b128 v[72:75], v81
	s_branch .LBB0_275

.LBB0_599:
	s_and_b32 s0, s8, 8
	v_mov_b64_e32 v[4:5], s[4:5]
	s_add_i32 s0, s0, s7
	v_mad_i64_i32 v[2:3], s[4:5], v2, s94, v[4:5]
	s_lshl_b32 s4, s0, 4
	s_ashr_i32 s5, s4, 31
	v_lshl_add_u64 v[2:3], s[4:5], 1, v[2:3]
	s_mov_b64 s[4:5], 0xe001000
	v_add_co_u32_e32 v6, vcc, 0xe001000, v2
	v_lshl_add_u64 v[4:5], v[2:3], 0, s[4:5]
	s_nop 0
	v_addc_co_u32_e32 v7, vcc, 0, v3, vcc
	global_load_dwordx4 v[2:5], v[4:5], off offset:16
	s_nop 0
	global_load_dwordx4 v[6:9], v[6:7], off
	s_lshr_b32 s1, s11, 6
	s_mulk_i32 s1, 0x3e00
	s_add_i32 s1, s1, 0
	v_mad_u32_u24 v0, v0, 48, s1
	s_waitcnt vmcnt(0)
	v_mov_b32_e32 v37, v204
	v_mov_b32_e32 v10, s59
	s_add_i32 s4, s0, s21
	s_ashr_i32 s5, s4, 31
	s_lshl_b64 s[22:23], s[4:5], 13
	v_mov_b32_e32 v11, v1
	s_mov_b32 s11, 0x200000
	v_mov_b32_e32 v36, 0
	v_mov_b32_e32 v38, 0
	v_mov_b32_e32 v39, 0
	v_mov_b32_e32 v40, 0
	v_mov_b32_e32 v41, 0
	s_waitcnt lgkmcnt(0)
	ds_write_b128 v0, v[2:5] offset:16
	ds_write_b128 v0, v[6:9]
	s_waitcnt lgkmcnt(0)
	ds_read_b64 v[2:3], v10
	v_readfirstlane_b32 s1, v37
	v_and_b32_e32 v136, 63, v37
	s_lshr_b32 s1, s1, 6
	v_lshl_or_b32 v4, s4, 6, v136
	s_mulk_i32 s1, 0x3e00
	v_ashrrev_i32_e32 v5, 31, v4
	s_add_i32 s1, s1, 0
	s_waitcnt lgkmcnt(0)
	v_readfirstlane_b32 s5, v3
	v_readfirstlane_b32 s4, v2
	v_and_b32_e32 v42, 15, v37
	v_and_b32_e32 v0, 48, v37
	v_lshl_add_u64 v[2:3], v[4:5], 4, s[4:5]
	s_add_u32 s4, s4, s22
	s_addc_u32 s5, s5, s23
	v_lshlrev_b32_e32 v10, 6, v42
	v_lshl_add_u64 v[4:5], s[4:5], 0, v[0:1]
	v_add_co_u32_e32 v2, vcc, s11, v2
	v_lshl_add_u64 v[6:7], v[4:5], 0, v[10:11]
	s_mov_b64 s[4:5], 0x240000
	v_addc_co_u32_e32 v3, vcc, 0, v3, vcc
	v_lshl_add_u64 v[8:9], v[6:7], 0, s[4:5]
	s_mov_b32 s4, 0x240000
	v_add_co_u32_e32 v10, vcc, s4, v6
	global_load_dwordx2 v[2:3], v[2:3], off
	s_nop 0
	global_load_dwordx4 v[28:31], v[8:9], off offset:1024
	global_load_dwordx4 v[20:23], v[8:9], off offset:2048
	global_load_dwordx4 v[12:15], v[8:9], off offset:3072
	s_mov_b64 s[36:37], vcc
	s_waitcnt lgkmcnt(0)
	v_add_co_u32_e32 v4, vcc, 0x241000, v6
	v_addc_co_u32_e64 v11, s[36:37], 0, v7, s[36:37]
	s_nop 0
	v_addc_co_u32_e32 v5, vcc, 0, v7, vcc
	global_load_dwordx4 v[32:35], v[10:11], off
	global_load_dwordx4 v[24:27], v[4:5], off
	global_load_dwordx4 v[16:19], v[4:5], off offset:1024
	s_nop 0
	global_load_dwordx4 v[8:11], v[4:5], off offset:2048
	s_nop 0
	global_load_dwordx4 v[4:7], v[4:5], off offset:3072
	v_add_u32_e32 v0, s1, v0
	v_cmp_gt_u32_e32 vcc, 32, v136
	v_mad_u32_u24 v158, v42, 48, v0
	s_and_saveexec_b64 s[4:5], vcc
	ds_read_b128 v[38:41], v158
	s_or_b64 exec, exec, s[4:5]
	s_waitcnt vmcnt(0) lgkmcnt(0)
	v_mfma_f32_16x16x32_bf16 v[44:47], v[38:41], v[32:35], 0
	v_bfe_u32 v0, v37, 4, 2
	v_lshlrev_b32_e32 v37, 2, v42
	v_mul_u32_u24_e32 v0, 0x840, v0
	v_mfma_f32_16x16x32_bf16 v[48:51], v[38:41], v[28:31], 0
	v_add3_u32 v37, s1, v37, v0
	v_add_u32_e32 v0, 0xc00, v37
	v_add_u32_e32 v137, 0x1000, v37
	v_mfma_f32_16x16x32_bf16 v[52:55], v[38:41], v[20:23], 0
	v_lshl_add_u32 v138, v136, 2, s1
	s_nop 2
	ds_write2_b32 v0, v44, v48 offset1:16
	ds_write2_b32 v0, v45, v49 offset0:132 offset1:148
	v_mfma_f32_16x16x32_bf16 v[56:59], v[38:41], v[12:15], 0
	ds_write2_b32 v137, v46, v50 offset0:8 offset1:24
	ds_write2_b32 v137, v47, v51 offset0:140 offset1:156
	s_nop 5
	ds_write2_b32 v0, v52, v56 offset0:32 offset1:48
	ds_write2_b32 v0, v53, v57 offset0:164 offset1:180
	v_mfma_f32_16x16x32_bf16 v[42:45], v[38:41], v[24:27], 0
	v_add_u32_e32 v139, 16, v138
	v_add_u32_e32 v140, 32, v138
	v_add_u32_e32 v141, 48, v138
	v_mfma_f32_16x16x32_bf16 v[46:49], v[38:41], v[16:19], 0
	ds_write2_b32 v137, v54, v58 offset0:40 offset1:56
	ds_write2_b32 v137, v55, v59 offset0:172 offset1:188
	s_nop 5
	ds_write2_b32 v0, v42, v46 offset0:64 offset1:80
	ds_write2_b32 v0, v43, v47 offset0:196 offset1:212
	ds_write2_b32 v137, v44, v48 offset0:72 offset1:88
	ds_write2_b32 v137, v45, v49 offset0:204 offset1:220
	v_mfma_f32_16x16x32_bf16 v[50:53], v[38:41], v[8:11], 0
	v_add_u32_e32 v146, 64, v138
	v_add_u32_e32 v147, 0x50, v138
	v_add_u32_e32 v148, 0x60, v138
	v_mfma_f32_16x16x32_bf16 v[38:41], v[38:41], v[4:7], 0
	s_nop 7
	ds_write2_b32 v0, v50, v38 offset0:96 offset1:112
	ds_write2_b32 v0, v51, v39 offset0:228 offset1:244
	ds_write2_b32 v137, v52, v40 offset0:104 offset1:120
	ds_write2_b32 v137, v53, v41 offset0:236 offset1:252
	s_waitcnt lgkmcnt(0)
	v_add_u32_e32 v149, 0x70, v138
	v_add_u32_e32 v150, 0x80, v138
	v_add_u32_e32 v151, 0x90, v138
	v_add_u32_e32 v152, 0xa0, v138
	v_add_u32_e32 v153, 0xb0, v138
	v_add_u32_e32 v154, 0xc0, v138
	v_add_u32_e32 v155, 0xd0, v138
	v_add_u32_e32 v156, 0xe0, v138
	v_add_u32_e32 v157, 0xf0, v138
	ds_read2st64_b32 v[134:135], v138 offset0:12 offset1:13
	ds_read2st64_b32 v[132:133], v139 offset0:14 offset1:15
	ds_read2st64_b32 v[130:131], v140 offset0:16 offset1:17
	ds_read2st64_b32 v[128:129], v141 offset0:18 offset1:19
	ds_read2st64_b32 v[124:125], v146 offset0:20 offset1:21
	ds_read2st64_b32 v[120:121], v147 offset0:22 offset1:23
	ds_read2st64_b32 v[116:117], v148 offset0:24 offset1:25
	ds_read2st64_b32 v[112:113], v149 offset0:26 offset1:27
	ds_read2st64_b32 v[108:109], v150 offset0:28 offset1:29
	ds_read2st64_b32 v[102:103], v151 offset0:30 offset1:31
	ds_read2st64_b32 v[98:99], v152 offset0:32 offset1:33
	ds_read2st64_b32 v[94:95], v153 offset0:34 offset1:35
	ds_read2st64_b32 v[88:89], v154 offset0:36 offset1:37
	ds_read2st64_b32 v[82:83], v155 offset0:38 offset1:39
	ds_read2st64_b32 v[76:77], v156 offset0:40 offset1:41
	ds_read2st64_b32 v[70:71], v157 offset0:42 offset1:43
	s_waitcnt lgkmcnt(0)
	v_mov_b32_e32 v37, 0
	v_mov_b32_e32 v38, 0
	v_mov_b32_e32 v39, 0
	s_and_saveexec_b64 s[4:5], vcc
	ds_read_b128 v[36:39], v158 offset:768
	s_or_b64 exec, exec, s[4:5]
	s_waitcnt lgkmcnt(0)
	v_mfma_f32_16x16x32_bf16 v[40:43], v[36:39], v[32:35], 0
	v_mfma_f32_16x16x32_bf16 v[44:47], v[36:39], v[28:31], 0
	s_nop 7
	ds_write2_b32 v0, v40, v44 offset1:16
	ds_write2_b32 v0, v41, v45 offset0:132 offset1:148
	ds_write2_b32 v137, v42, v46 offset0:8 offset1:24
	v_mfma_f32_16x16x32_bf16 v[48:51], v[36:39], v[20:23], 0
	v_mfma_f32_16x16x32_bf16 v[52:55], v[36:39], v[12:15], 0
	ds_write2_b32 v137, v43, v47 offset0:140 offset1:156
	s_nop 6
	ds_write2_b32 v0, v48, v52 offset0:32 offset1:48
	ds_write2_b32 v0, v49, v53 offset0:164 offset1:180
	v_mfma_f32_16x16x32_bf16 v[56:59], v[36:39], v[24:27], 0
	v_mfma_f32_16x16x32_bf16 v[40:43], v[36:39], v[16:19], 0
	ds_write2_b32 v137, v50, v54 offset0:40 offset1:56
	ds_write2_b32 v137, v51, v55 offset0:172 offset1:188
	s_nop 5
	ds_write2_b32 v0, v56, v40 offset0:64 offset1:80
	ds_write2_b32 v0, v57, v41 offset0:196 offset1:212
	ds_write2_b32 v137, v58, v42 offset0:72 offset1:88
	ds_write2_b32 v137, v59, v43 offset0:204 offset1:220
	v_mfma_f32_16x16x32_bf16 v[44:47], v[36:39], v[8:11], 0
	v_mov_b32_e32 v40, 0
	v_mov_b32_e32 v41, 0
	v_mfma_f32_16x16x32_bf16 v[36:39], v[36:39], v[4:7], 0
	s_nop 7
	ds_write2_b32 v0, v44, v36 offset0:96 offset1:112
	ds_write2_b32 v0, v45, v37 offset0:228 offset1:244
	ds_write2_b32 v137, v46, v38 offset0:104 offset1:120
	ds_write2_b32 v137, v47, v39 offset0:236 offset1:252
	s_waitcnt lgkmcnt(0)
	ds_read2st64_b32 v[126:127], v138 offset0:12 offset1:13
	ds_read2st64_b32 v[122:123], v139 offset0:14 offset1:15
	ds_read2st64_b32 v[118:119], v140 offset0:16 offset1:17
	ds_read2st64_b32 v[114:115], v141 offset0:18 offset1:19
	ds_read2st64_b32 v[110:111], v146 offset0:20 offset1:21
	ds_read2st64_b32 v[104:105], v147 offset0:22 offset1:23
	ds_read2st64_b32 v[96:97], v148 offset0:24 offset1:25
	ds_read2st64_b32 v[90:91], v149 offset0:26 offset1:27
	ds_read2st64_b32 v[84:85], v150 offset0:28 offset1:29
	ds_read2st64_b32 v[78:79], v151 offset0:30 offset1:31
	ds_read2st64_b32 v[72:73], v152 offset0:32 offset1:33
	ds_read2st64_b32 v[66:67], v153 offset0:34 offset1:35
	ds_read2st64_b32 v[62:63], v154 offset0:36 offset1:37
	ds_read2st64_b32 v[58:59], v155 offset0:38 offset1:39
	ds_read2st64_b32 v[54:55], v156 offset0:40 offset1:41
	ds_read2st64_b32 v[50:51], v157 offset0:42 offset1:43
	s_waitcnt lgkmcnt(0)
	v_mov_b32_e32 v36, 0
	v_mov_b32_e32 v38, 0
	v_mov_b32_e32 v39, 0
	s_and_saveexec_b64 s[4:5], vcc
	ds_read_b128 v[38:41], v158 offset:1536
	s_or_b64 exec, exec, s[4:5]
	s_waitcnt lgkmcnt(0)
	v_mfma_f32_16x16x32_bf16 v[42:45], v[38:41], v[32:35], 0
	v_mov_b32_e32 v37, 0
	v_mfma_f32_16x16x32_bf16 v[46:49], v[38:41], v[28:31], 0
	s_nop 7
	ds_write2_b32 v0, v42, v46 offset1:16
	ds_write2_b32 v0, v43, v47 offset0:132 offset1:148
	ds_write2_b32 v137, v44, v48 offset0:8 offset1:24
	v_mfma_f32_16x16x32_bf16 v[160:163], v[38:41], v[20:23], 0
	v_mfma_f32_16x16x32_bf16 v[164:167], v[38:41], v[12:15], 0
	ds_write2_b32 v137, v45, v49 offset0:140 offset1:156
	s_nop 6
	ds_write2_b32 v0, v160, v164 offset0:32 offset1:48
	ds_write2_b32 v0, v161, v165 offset0:164 offset1:180
	v_mfma_f32_16x16x32_bf16 v[168:171], v[38:41], v[24:27], 0
	v_mfma_f32_16x16x32_bf16 v[42:45], v[38:41], v[16:19], 0
	ds_write2_b32 v137, v162, v166 offset0:40 offset1:56
	ds_write2_b32 v137, v163, v167 offset0:172 offset1:188
	s_nop 5
	ds_write2_b32 v0, v168, v42 offset0:64 offset1:80
	ds_write2_b32 v0, v169, v43 offset0:196 offset1:212
	ds_write2_b32 v137, v170, v44 offset0:72 offset1:88
	ds_write2_b32 v137, v171, v45 offset0:204 offset1:220
	v_mfma_f32_16x16x32_bf16 v[46:49], v[38:41], v[8:11], 0
	v_mfma_f32_16x16x32_bf16 v[38:41], v[38:41], v[4:7], 0
	s_nop 7
	ds_write2_b32 v0, v46, v38 offset0:96 offset1:112
	ds_write2_b32 v0, v47, v39 offset0:228 offset1:244
	ds_write2_b32 v137, v48, v40 offset0:104 offset1:120
	ds_write2_b32 v137, v49, v41 offset0:236 offset1:252
	s_waitcnt lgkmcnt(0)
	ds_read2st64_b32 v[106:107], v138 offset0:12 offset1:13
	ds_read2st64_b32 v[100:101], v139 offset0:14 offset1:15
	ds_read2st64_b32 v[92:93], v140 offset0:16 offset1:17
	ds_read2st64_b32 v[86:87], v141 offset0:18 offset1:19
	ds_read2st64_b32 v[80:81], v146 offset0:20 offset1:21
	ds_read2st64_b32 v[74:75], v147 offset0:22 offset1:23
	ds_read2st64_b32 v[68:69], v148 offset0:24 offset1:25
	ds_read2st64_b32 v[64:65], v149 offset0:26 offset1:27
	ds_read2st64_b32 v[60:61], v150 offset0:28 offset1:29
	ds_read2st64_b32 v[56:57], v151 offset0:30 offset1:31
	ds_read2st64_b32 v[52:53], v152 offset0:32 offset1:33
	ds_read2st64_b32 v[48:49], v153 offset0:34 offset1:35
	ds_read2st64_b32 v[46:47], v154 offset0:36 offset1:37
	ds_read2st64_b32 v[44:45], v155 offset0:38 offset1:39
	ds_read2st64_b32 v[42:43], v156 offset0:40 offset1:41
	ds_read2st64_b32 v[40:41], v157 offset0:42 offset1:43
	s_waitcnt lgkmcnt(0)
	v_mov_b32_e32 v38, 0
	v_mov_b32_e32 v39, 0
	s_and_saveexec_b64 s[4:5], vcc
	ds_read_b128 v[36:39], v158 offset:2304
	s_or_b64 exec, exec, s[4:5]
	v_mul_f32_e32 v158, 0, v3
	v_fma_f32 v159, 0, v2, v158
	v_add_f32_e32 v135, v159, v135
	v_fma_f32 v158, v2, 0, -v158
	v_mul_f32_e32 v159, v2, v135
	v_add_f32_e32 v134, v158, v134
	v_mul_f32_e32 v135, v3, v135
	v_fmac_f32_e32 v159, v3, v134
	v_fma_f32 v134, v2, v134, -v135
	v_add_f32_e32 v132, v132, v134
	v_add_f32_e32 v133, v133, v159
	v_fma_f32 v134, v3, v132, v131
	v_fma_f32 v130, v2, v132, v130
	v_fma_f32 v130, -v3, v133, v130
	v_fma_f32 v131, v2, v133, v134
	v_fma_f32 v132, v3, v130, v129
	v_fma_f32 v128, v2, v130, v128
	v_fma_f32 v128, -v3, v131, v128
	v_fma_f32 v129, v2, v131, v132
	v_fma_f32 v130, v3, v128, v125
	v_fma_f32 v124, v2, v128, v124
	v_fma_f32 v124, -v3, v129, v124
	v_fma_f32 v125, v2, v129, v130
	v_fma_f32 v128, v3, v124, v121
	v_fma_f32 v120, v2, v124, v120
	v_fma_f32 v120, -v3, v125, v120
	v_fma_f32 v121, v2, v125, v128
	v_fma_f32 v124, v3, v120, v117
	v_fma_f32 v116, v2, v120, v116
	v_fma_f32 v116, -v3, v121, v116
	v_fma_f32 v117, v2, v121, v124
	v_fma_f32 v120, v3, v116, v113
	v_fma_f32 v112, v2, v116, v112
	v_fma_f32 v112, -v3, v117, v112
	v_fma_f32 v113, v2, v117, v120
	v_fma_f32 v116, v3, v112, v109
	v_fma_f32 v108, v2, v112, v108
	v_fma_f32 v108, -v3, v113, v108
	v_fma_f32 v109, v2, v113, v116
	v_fma_f32 v112, v3, v108, v103
	v_fma_f32 v102, v2, v108, v102
	v_fma_f32 v102, -v3, v109, v102
	v_fma_f32 v103, v2, v109, v112
	v_fma_f32 v108, v3, v102, v99
	v_fma_f32 v98, v2, v102, v98
	v_fma_f32 v98, -v3, v103, v98
	v_fma_f32 v99, v2, v103, v108
	v_fma_f32 v102, v3, v98, v95
	v_fma_f32 v94, v2, v98, v94
	v_fma_f32 v94, -v3, v99, v94
	v_fma_f32 v95, v2, v99, v102
	v_fma_f32 v98, v3, v94, v89
	v_fma_f32 v88, v2, v94, v88
	v_fma_f32 v88, -v3, v95, v88
	v_fma_f32 v89, v2, v95, v98
	v_fma_f32 v94, v3, v88, v83
	v_fma_f32 v82, v2, v88, v82
	v_fma_f32 v82, -v3, v89, v82
	v_fma_f32 v83, v2, v89, v94
	v_fma_f32 v88, v3, v82, v77
	v_fma_f32 v76, v2, v82, v76
	v_fma_f32 v76, -v3, v83, v76
	v_fma_f32 v77, v2, v83, v88
	v_fma_f32 v82, v3, v76, v71
	v_fma_f32 v70, v2, v76, v70
	v_fma_f32 v70, -v3, v77, v70
	v_fma_f32 v71, v2, v77, v82
	v_mul_f32_e32 v76, v3, v70
	v_fmac_f32_e32 v76, v2, v71
	v_mul_f32_e32 v71, v3, v71
	v_add_f32_e32 v76, v76, v127
	v_fma_f32 v70, v2, v70, -v71
	v_mul_f32_e32 v77, v2, v76
	v_add_f32_e32 v70, v70, v126
	v_mul_f32_e32 v76, v3, v76
	v_fmac_f32_e32 v77, v3, v70
	v_fma_f32 v70, v2, v70, -v76
	v_add_f32_e32 v70, v122, v70
	v_add_f32_e32 v71, v123, v77
	v_fma_f32 v76, v3, v70, v119
	v_fma_f32 v70, v2, v70, v118
	v_fma_f32 v70, -v3, v71, v70
	v_fma_f32 v76, v2, v71, v76
	v_fma_f32 v71, v3, v70, v115
	v_fma_f32 v70, v2, v70, v114
	v_fma_f32 v70, -v3, v76, v70
	v_fma_f32 v71, v2, v76, v71
	v_fma_f32 v76, v3, v70, v111
	v_fma_f32 v70, v2, v70, v110
	v_fma_f32 v70, -v3, v71, v70
	v_fma_f32 v76, v2, v71, v76
	v_fma_f32 v71, v3, v70, v105
	v_fma_f32 v70, v2, v70, v104
	v_fma_f32 v70, -v3, v76, v70
	v_fma_f32 v71, v2, v76, v71
	v_fma_f32 v76, v3, v70, v97
	v_fma_f32 v70, v2, v70, v96
	v_fma_f32 v70, -v3, v71, v70
	v_fma_f32 v76, v2, v71, v76
	v_fma_f32 v71, v3, v70, v91
	v_fma_f32 v70, v2, v70, v90
	v_fma_f32 v70, -v3, v76, v70
	v_fma_f32 v71, v2, v76, v71
	v_fma_f32 v76, v3, v70, v85
	v_fma_f32 v70, v2, v70, v84
	v_fma_f32 v70, -v3, v71, v70
	v_fma_f32 v76, v2, v71, v76
	v_fma_f32 v71, v3, v70, v79
	v_fma_f32 v70, v2, v70, v78
	v_fma_f32 v70, -v3, v76, v70
	v_fma_f32 v71, v2, v76, v71
	v_fma_f32 v76, v3, v70, v73
	v_fma_f32 v70, v2, v70, v72
	v_fma_f32 v70, -v3, v71, v70
	v_fma_f32 v73, v2, v71, v76
	v_fma_f32 v71, v3, v70, v67
	v_fma_f32 v66, v2, v70, v66
	v_fma_f32 v66, -v3, v73, v66
	v_fma_f32 v67, v2, v73, v71
	v_fma_f32 v70, v3, v66, v63
	v_fma_f32 v62, v2, v66, v62
	v_fma_f32 v62, -v3, v67, v62
	v_fma_f32 v63, v2, v67, v70
	v_fma_f32 v66, v3, v62, v59
	v_fma_f32 v58, v2, v62, v58
	v_fma_f32 v58, -v3, v63, v58
	v_fma_f32 v59, v2, v63, v66
	v_fma_f32 v62, v3, v58, v55
	v_fma_f32 v54, v2, v58, v54
	v_fma_f32 v54, -v3, v59, v54
	v_fma_f32 v55, v2, v59, v62
	v_fma_f32 v58, v3, v54, v51
	v_fma_f32 v50, v2, v54, v50
	v_fma_f32 v50, -v3, v55, v50
	v_fma_f32 v51, v2, v55, v58
	v_mul_f32_e32 v54, v3, v50
	v_fmac_f32_e32 v54, v2, v51
	v_mul_f32_e32 v51, v3, v51
	s_waitcnt lgkmcnt(14)
	v_add_f32_e32 v54, v54, v107
	v_fma_f32 v50, v2, v50, -v51
	v_mul_f32_e32 v55, v2, v54
	v_add_f32_e32 v50, v50, v106
	v_mul_f32_e32 v54, v3, v54
	v_fmac_f32_e32 v55, v3, v50
	v_fma_f32 v50, v2, v50, -v54
	v_add_f32_e32 v50, v100, v50
	v_add_f32_e32 v51, v101, v55
	s_waitcnt lgkmcnt(13)
	v_fma_f32 v54, v3, v50, v93
	v_fma_f32 v50, v2, v50, v92
	v_fma_f32 v50, -v3, v51, v50
	v_fma_f32 v54, v2, v51, v54
	s_waitcnt lgkmcnt(12)
	v_fma_f32 v51, v3, v50, v87
	v_fma_f32 v50, v2, v50, v86
	v_fma_f32 v50, -v3, v54, v50
	v_fma_f32 v51, v2, v54, v51
	s_waitcnt lgkmcnt(11)
	v_fma_f32 v54, v3, v50, v81
	v_fma_f32 v50, v2, v50, v80
	v_fma_f32 v50, -v3, v51, v50
	v_fma_f32 v54, v2, v51, v54
	s_waitcnt lgkmcnt(10)
	v_fma_f32 v51, v3, v50, v75
	v_fma_f32 v50, v2, v50, v74
	v_fma_f32 v50, -v3, v54, v50
	v_fma_f32 v51, v2, v54, v51
	s_waitcnt lgkmcnt(9)
	v_fma_f32 v54, v3, v50, v69
	v_fma_f32 v50, v2, v50, v68
	v_fma_f32 v50, -v3, v51, v50
	v_fma_f32 v54, v2, v51, v54
	s_waitcnt lgkmcnt(8)
	v_fma_f32 v51, v3, v50, v65
	v_fma_f32 v50, v2, v50, v64
	v_fma_f32 v50, -v3, v54, v50
	v_fma_f32 v51, v2, v54, v51
	s_waitcnt lgkmcnt(7)
	v_fma_f32 v54, v3, v50, v61
	v_fma_f32 v50, v2, v50, v60
	v_fma_f32 v50, -v3, v51, v50
	v_fma_f32 v54, v2, v51, v54
	s_waitcnt lgkmcnt(6)
	v_fma_f32 v51, v3, v50, v57
	v_fma_f32 v50, v2, v50, v56
	v_fma_f32 v50, -v3, v54, v50
	v_fma_f32 v51, v2, v54, v51
	s_waitcnt lgkmcnt(5)
	v_fma_f32 v54, v3, v50, v53
	v_fma_f32 v50, v2, v50, v52
	v_fma_f32 v50, -v3, v51, v50
	v_fma_f32 v53, v2, v51, v54
	s_waitcnt lgkmcnt(4)
	v_fma_f32 v51, v3, v50, v49
	v_fma_f32 v48, v2, v50, v48
	v_fma_f32 v48, -v3, v53, v48
	v_fma_f32 v49, v2, v53, v51
	s_waitcnt lgkmcnt(3)
	v_fma_f32 v50, v3, v48, v47
	v_fma_f32 v46, v2, v48, v46
	v_fma_f32 v46, -v3, v49, v46
	v_fma_f32 v47, v2, v49, v50
	s_waitcnt lgkmcnt(2)
	v_fma_f32 v48, v3, v46, v45
	v_fma_f32 v44, v2, v46, v44
	v_fma_f32 v44, -v3, v47, v44
	v_fma_f32 v45, v2, v47, v48
	s_waitcnt lgkmcnt(0)
	v_mfma_f32_16x16x32_bf16 v[32:35], v[36:39], v[32:35], 0
	v_fma_f32 v46, v3, v44, v43
	v_fma_f32 v42, v2, v44, v42
	v_fma_f32 v42, -v3, v45, v42
	v_fma_f32 v43, v2, v45, v46
	v_mfma_f32_16x16x32_bf16 v[28:31], v[36:39], v[28:31], 0
	v_mfma_f32_16x16x32_bf16 v[20:23], v[36:39], v[20:23], 0
	s_nop 1
	ds_write2_b32 v0, v32, v28 offset1:16
	ds_write2_b32 v0, v33, v29 offset0:132 offset1:148
	ds_write2_b32 v137, v34, v30 offset0:8 offset1:24
	v_mfma_f32_16x16x32_bf16 v[12:15], v[36:39], v[12:15], 0
	ds_write2_b32 v137, v35, v31 offset0:140 offset1:156
	s_nop 6
	ds_write2_b32 v0, v20, v12 offset0:32 offset1:48
	ds_write2_b32 v0, v21, v13 offset0:164 offset1:180
	v_mfma_f32_16x16x32_bf16 v[24:27], v[36:39], v[24:27], 0
	v_fma_f32 v44, v3, v42, v41
	v_fma_f32 v40, v2, v42, v40
	v_fma_f32 v40, -v3, v43, v40
	v_fma_f32 v41, v2, v43, v44
	s_lshl_b32 s11, s10, 1
	s_mul_i32 s1, s10, 0x88
	v_mfma_f32_16x16x32_bf16 v[16:19], v[36:39], v[16:19], 0
	ds_write2_b32 v137, v22, v14 offset0:40 offset1:56
	ds_write2_b32 v137, v23, v15 offset0:172 offset1:188
	s_nop 5
	ds_write2_b32 v0, v24, v16 offset0:64 offset1:80
	ds_write2_b32 v0, v25, v17 offset0:196 offset1:212
	ds_write2_b32 v137, v26, v18 offset0:72 offset1:88
	ds_write2_b32 v137, v27, v19 offset0:204 offset1:220
	v_mfma_f32_16x16x32_bf16 v[8:11], v[36:39], v[8:11], 0
	s_ashr_i32 s10, s9, 31
	s_mul_hi_i32 s5, s11, 0x44
	s_add_u32 s4, s1, s9
	v_mfma_f32_16x16x32_bf16 v[4:7], v[36:39], v[4:7], 0
	s_nop 7
	ds_write2_b32 v0, v8, v4 offset0:96 offset1:112
	ds_write2_b32 v0, v9, v5 offset0:228 offset1:244
	ds_write2_b32 v137, v10, v6 offset0:104 offset1:120
	ds_write2_b32 v137, v11, v7 offset0:236 offset1:252
	s_waitcnt lgkmcnt(0)
	v_mul_f32_e32 v0, v3, v41
	ds_read2st64_b32 v[4:5], v138 offset0:12 offset1:13
	ds_read2st64_b32 v[6:7], v139 offset0:14 offset1:15
	ds_read2st64_b32 v[8:9], v140 offset0:16 offset1:17
	ds_read2st64_b32 v[10:11], v141 offset0:18 offset1:19
	ds_read2st64_b32 v[12:13], v146 offset0:20 offset1:21
	ds_read2st64_b32 v[14:15], v147 offset0:22 offset1:23
	ds_read2st64_b32 v[16:17], v148 offset0:24 offset1:25
	ds_read2st64_b32 v[18:19], v149 offset0:26 offset1:27
	ds_read2st64_b32 v[20:21], v150 offset0:28 offset1:29
	ds_read2st64_b32 v[22:23], v151 offset0:30 offset1:31
	ds_read2st64_b32 v[24:25], v152 offset0:32 offset1:33
	ds_read2st64_b32 v[26:27], v153 offset0:34 offset1:35
	ds_read2st64_b32 v[28:29], v154 offset0:36 offset1:37
	ds_read2st64_b32 v[30:31], v155 offset0:38 offset1:39
	ds_read2st64_b32 v[32:33], v156 offset0:40 offset1:41
	ds_read2st64_b32 v[34:35], v157 offset0:42 offset1:43
	v_fma_f32 v0, v2, v40, -v0
	s_waitcnt lgkmcnt(14)
	v_add_f32_e32 v0, v0, v4
	v_mul_f32_e32 v4, v3, v40
	v_fmac_f32_e32 v4, v2, v41
	v_add_f32_e32 v4, v4, v5
	v_mul_f32_e32 v5, v3, v4
	v_mul_f32_e32 v4, v2, v4
	v_fmac_f32_e32 v4, v3, v0
	v_fma_f32 v5, v2, v0, -v5
	v_add_f32_e32 v0, v7, v4
	v_add_f32_e32 v5, v6, v5
	s_waitcnt lgkmcnt(13)
	v_fma_f32 v4, -v0, v3, v8
	v_fma_f32 v0, v0, v2, v9
	v_fma_f32 v0, v5, v3, v0
	v_fma_f32 v4, v5, v2, v4
	s_waitcnt lgkmcnt(12)
	v_fma_f32 v5, -v0, v3, v10
	v_fma_f32 v0, v0, v2, v11
	v_fma_f32 v0, v4, v3, v0
	v_fma_f32 v5, v4, v2, v5
	s_waitcnt lgkmcnt(11)
	v_fma_f32 v4, -v0, v3, v12
	v_fma_f32 v0, v0, v2, v13
	v_fma_f32 v0, v5, v3, v0
	v_fma_f32 v4, v5, v2, v4
	s_waitcnt lgkmcnt(10)
	v_fma_f32 v5, -v0, v3, v14
	v_fma_f32 v0, v0, v2, v15
	v_fma_f32 v0, v4, v3, v0
	v_fma_f32 v5, v4, v2, v5
	s_waitcnt lgkmcnt(9)
	v_fma_f32 v4, -v0, v3, v16
	v_fma_f32 v0, v0, v2, v17
	v_fma_f32 v0, v5, v3, v0
	v_fma_f32 v4, v5, v2, v4
	s_waitcnt lgkmcnt(8)
	v_fma_f32 v5, -v0, v3, v18
	v_fma_f32 v0, v0, v2, v19
	v_fma_f32 v0, v4, v3, v0
	v_fma_f32 v5, v4, v2, v5
	s_waitcnt lgkmcnt(7)
	v_fma_f32 v4, -v0, v3, v20
	v_fma_f32 v0, v0, v2, v21
	v_fma_f32 v0, v5, v3, v0
	v_fma_f32 v4, v5, v2, v4
	s_waitcnt lgkmcnt(6)
	v_fma_f32 v5, -v0, v3, v22
	v_fma_f32 v0, v0, v2, v23
	v_fma_f32 v0, v4, v3, v0
	v_fma_f32 v5, v4, v2, v5
	s_waitcnt lgkmcnt(5)
	v_fma_f32 v4, -v0, v3, v24
	v_fma_f32 v0, v0, v2, v25
	v_fma_f32 v0, v5, v3, v0
	v_fma_f32 v4, v5, v2, v4
	s_waitcnt lgkmcnt(4)
	v_fma_f32 v5, -v0, v3, v26
	v_fma_f32 v0, v0, v2, v27
	v_fma_f32 v0, v4, v3, v0
	v_fma_f32 v5, v4, v2, v5
	s_waitcnt lgkmcnt(3)
	v_fma_f32 v4, -v0, v3, v28
	v_fma_f32 v0, v0, v2, v29
	v_fma_f32 v0, v5, v3, v0
	v_fma_f32 v4, v5, v2, v4
	s_waitcnt lgkmcnt(2)
	v_fma_f32 v5, -v0, v3, v30
	v_fma_f32 v0, v0, v2, v31
	v_fma_f32 v0, v4, v3, v0
	v_fma_f32 v5, v4, v2, v5
	s_waitcnt lgkmcnt(1)
	v_fma_f32 v4, v3, v5, v33
	v_fma_f32 v6, v2, v5, v32
	v_fma_f32 v6, -v3, v0, v6
	v_fma_f32 v0, v2, v0, v4
	v_mul_f32_e32 v4, v3, v0
	v_mul_f32_e32 v3, v3, v6
	v_fmac_f32_e32 v3, v2, v0
	s_waitcnt lgkmcnt(0)
	v_mov_b32_e32 v0, s59
	v_fma_f32 v4, v2, v6, -v4
	s_waitcnt lgkmcnt(0)
	v_add_f32_e32 v5, v35, v3
	ds_read_b64 v[2:3], v0
	s_addc_u32 s5, s5, s10
	s_ashr_i32 s1, s0, 31
	s_lshl_b64 s[22:23], s[4:5], 10
	s_lshl_b64 s[4:5], s[0:1], 6
	s_add_u32 s1, s22, s4
	s_addc_u32 s17, s23, s5
	v_or_b32_e32 v6, s1, v136
	v_mov_b32_e32 v7, s17
	s_waitcnt lgkmcnt(0)
	v_readfirstlane_b32 s1, v3
	v_readfirstlane_b32 s17, v2
	v_add_f32_e32 v4, v34, v4
	v_mov_b32_e32 v3, s1
	v_mov_b32_e32 v2, s17
	v_lshl_add_u64 v[2:3], v[6:7], 3, v[2:3]
	s_mov_b32 s1, 0xc00000
	v_add_co_u32_e32 v2, vcc, s1, v2
	v_mov_b32_e32 v42, v204
	s_nop 0
	v_addc_co_u32_e32 v3, vcc, 0, v3, vcc
	global_store_dwordx2 v[2:3], v[4:5], off
	ds_read_b64 v[2:3], v0
	v_readfirstlane_b32 s1, v42
	s_lshr_b32 s1, s1, 6
	s_mulk_i32 s1, 0x3e00
	s_add_i32 s17, s1, 0
	v_readlane_b32 s1, v244, 25
	v_and_b32_e32 v136, 63, v42
	s_add_i32 s0, s0, s1
	s_waitcnt lgkmcnt(0)
	v_readfirstlane_b32 s22, v2
	v_lshl_or_b32 v2, s0, 6, v136
	v_readfirstlane_b32 s23, v3
	v_ashrrev_i32_e32 v3, 31, v2
	s_mov_b32 s1, 0x200000
	v_lshl_add_u64 v[2:3], v[2:3], 4, s[22:23]
	v_add_co_u32_e32 v2, vcc, s1, v2
	s_ashr_i32 s1, s0, 31
	s_lshl_b64 s[0:1], s[0:1], 13
	s_add_u32 s0, s22, s0
	v_and_b32_e32 v37, 15, v42
	s_addc_u32 s1, s23, s1
	v_and_b32_e32 v0, 48, v42
	v_lshl_add_u64 v[4:5], s[0:1], 0, v[0:1]
	v_lshlrev_b32_e32 v6, 6, v37
	v_mov_b32_e32 v7, v1
	v_lshl_add_u64 v[6:7], v[4:5], 0, v[6:7]
	s_mov_b64 s[0:1], 0x240000
	v_addc_co_u32_e32 v3, vcc, 0, v3, vcc
	v_lshl_add_u64 v[8:9], v[6:7], 0, s[0:1]
	s_mov_b32 s0, 0x240000
	v_add_co_u32_e32 v10, vcc, s0, v6
	global_load_dwordx2 v[2:3], v[2:3], off
	s_nop 0
	global_load_dwordx4 v[28:31], v[8:9], off offset:1024
	global_load_dwordx4 v[24:27], v[8:9], off offset:2048
	global_load_dwordx4 v[16:19], v[8:9], off offset:3072
	v_addc_co_u32_e32 v11, vcc, 0, v7, vcc
	s_waitcnt lgkmcnt(0)
	v_add_co_u32_e32 v4, vcc, 0x241000, v6
	v_mul_u32_u24_e32 v38, 48, v37
	s_nop 0
	v_addc_co_u32_e32 v5, vcc, 0, v7, vcc
	global_load_dwordx4 v[32:35], v[10:11], off
	global_load_dwordx4 v[20:23], v[4:5], off
	global_load_dwordx4 v[12:15], v[4:5], off offset:1024
	s_nop 0
	global_load_dwordx4 v[8:11], v[4:5], off offset:2048
	s_nop 0
	global_load_dwordx4 v[4:7], v[4:5], off offset:3072
	v_cmp_gt_u32_e32 vcc, 32, v136
	v_mov_b32_e32 v36, 0
	v_add3_u32 v159, s17, v38, v0
	v_mov_b32_e32 v38, 0
	v_mov_b32_e32 v39, 0
	v_mov_b32_e32 v40, 0
	v_mov_b32_e32 v41, 0
	s_and_saveexec_b64 s[0:1], vcc
	ds_read_b128 v[38:41], v159 offset:2304
	s_or_b64 exec, exec, s[0:1]
	s_waitcnt vmcnt(0) lgkmcnt(0)
	v_mfma_f32_16x16x32_bf16 v[44:47], v[38:41], v[32:35], 0
	v_bfe_u32 v43, v42, 4, 2
	v_lshlrev_b32_e32 v37, 2, v37
	v_mul_u32_u24_e32 v43, 0x840, v43
	v_mfma_f32_16x16x32_bf16 v[48:51], v[38:41], v[28:31], 0
	v_add3_u32 v37, s17, v37, v43
	v_add_u32_e32 v137, 0xc00, v37
	v_add_u32_e32 v138, 0x1000, v37
	v_mfma_f32_16x16x32_bf16 v[52:55], v[38:41], v[24:27], 0
	v_lshl_add_u32 v139, v136, 2, s17
	s_nop 2
	ds_write2_b32 v137, v44, v48 offset1:16
	ds_write2_b32 v137, v45, v49 offset0:132 offset1:148
	v_mfma_f32_16x16x32_bf16 v[56:59], v[38:41], v[16:19], 0
	ds_write2_b32 v138, v46, v50 offset0:8 offset1:24
	ds_write2_b32 v138, v47, v51 offset0:140 offset1:156
	s_nop 5
	ds_write2_b32 v137, v52, v56 offset0:32 offset1:48
	ds_write2_b32 v137, v53, v57 offset0:164 offset1:180
	v_mfma_f32_16x16x32_bf16 v[60:63], v[38:41], v[20:23], 0
	v_add_u32_e32 v140, 0xf0, v139
	v_add_u32_e32 v141, 0xe0, v139
	v_add_u32_e32 v146, 0xd0, v139
	v_mfma_f32_16x16x32_bf16 v[44:47], v[38:41], v[12:15], 0
	ds_write2_b32 v138, v54, v58 offset0:40 offset1:56
	ds_write2_b32 v138, v55, v59 offset0:172 offset1:188
	s_nop 5
	ds_write2_b32 v137, v60, v44 offset0:64 offset1:80
	ds_write2_b32 v137, v61, v45 offset0:196 offset1:212
	ds_write2_b32 v138, v62, v46 offset0:72 offset1:88
	ds_write2_b32 v138, v63, v47 offset0:204 offset1:220
	v_mfma_f32_16x16x32_bf16 v[48:51], v[38:41], v[8:11], 0
	v_add_u32_e32 v147, 0xc0, v139
	v_add_u32_e32 v148, 0xb0, v139
	v_add_u32_e32 v149, 0xa0, v139
	v_mfma_f32_16x16x32_bf16 v[38:41], v[38:41], v[4:7], 0
	s_nop 7
	ds_write2_b32 v137, v48, v38 offset0:96 offset1:112
	ds_write2_b32 v137, v49, v39 offset0:228 offset1:244
	ds_write2_b32 v138, v50, v40 offset0:104 offset1:120
	ds_write2_b32 v138, v51, v41 offset0:236 offset1:252
	s_waitcnt lgkmcnt(0)
	v_add_u32_e32 v150, 0x90, v139
	v_add_u32_e32 v151, 0x80, v139
	v_add_u32_e32 v152, 0x70, v139
	v_add_u32_e32 v153, 0x60, v139
	v_add_u32_e32 v154, 0x50, v139
	v_add_u32_e32 v155, 64, v139
	v_add_u32_e32 v156, 48, v139
	v_add_u32_e32 v157, 32, v139
	v_add_u32_e32 v158, 16, v139
	ds_read2st64_b32 v[134:135], v140 offset0:42 offset1:43
	ds_read2st64_b32 v[132:133], v141 offset0:40 offset1:41
	ds_read2st64_b32 v[130:131], v146 offset0:38 offset1:39
	ds_read2st64_b32 v[126:127], v147 offset0:36 offset1:37
	ds_read2st64_b32 v[122:123], v148 offset0:34 offset1:35
	ds_read2st64_b32 v[118:119], v149 offset0:32 offset1:33
	ds_read2st64_b32 v[116:117], v150 offset0:30 offset1:31
	ds_read2st64_b32 v[112:113], v151 offset0:28 offset1:29
	ds_read2st64_b32 v[108:109], v152 offset0:26 offset1:27
	ds_read2st64_b32 v[102:103], v153 offset0:24 offset1:25
	ds_read2st64_b32 v[96:97], v154 offset0:22 offset1:23
	ds_read2st64_b32 v[90:91], v155 offset0:20 offset1:21
	ds_read2st64_b32 v[86:87], v156 offset0:18 offset1:19
	ds_read2st64_b32 v[82:83], v157 offset0:16 offset1:17
	ds_read2st64_b32 v[76:77], v158 offset0:14 offset1:15
	ds_read2st64_b32 v[70:71], v139 offset0:12 offset1:13
	s_waitcnt lgkmcnt(0)
	v_mov_b32_e32 v37, 0
	v_mov_b32_e32 v38, 0
	v_mov_b32_e32 v39, 0
	s_and_saveexec_b64 s[0:1], vcc
	v_or_b32_e32 v36, 0xfffff0, v42
	v_mul_i32_i24_e32 v36, 48, v36
	v_add3_u32 v0, s17, v36, v0
	ds_read_b128 v[36:39], v0 offset:2304
	s_or_b64 exec, exec, s[0:1]
	s_waitcnt lgkmcnt(0)
	v_mfma_f32_16x16x32_bf16 v[40:43], v[36:39], v[32:35], 0
	v_mfma_f32_16x16x32_bf16 v[44:47], v[36:39], v[28:31], 0
	s_nop 7
	ds_write2_b32 v137, v40, v44 offset1:16
	ds_write2_b32 v137, v41, v45 offset0:132 offset1:148
	ds_write2_b32 v138, v42, v46 offset0:8 offset1:24
	v_mfma_f32_16x16x32_bf16 v[48:51], v[36:39], v[24:27], 0
	v_mfma_f32_16x16x32_bf16 v[52:55], v[36:39], v[16:19], 0
	ds_write2_b32 v138, v43, v47 offset0:140 offset1:156
	s_nop 6
	ds_write2_b32 v137, v48, v52 offset0:32 offset1:48
	ds_write2_b32 v137, v49, v53 offset0:164 offset1:180
	v_mfma_f32_16x16x32_bf16 v[56:59], v[36:39], v[20:23], 0
	v_mfma_f32_16x16x32_bf16 v[40:43], v[36:39], v[12:15], 0
	ds_write2_b32 v138, v50, v54 offset0:40 offset1:56
	ds_write2_b32 v138, v51, v55 offset0:172 offset1:188
	s_nop 5
	ds_write2_b32 v137, v56, v40 offset0:64 offset1:80
	ds_write2_b32 v137, v57, v41 offset0:196 offset1:212
	ds_write2_b32 v138, v58, v42 offset0:72 offset1:88
	ds_write2_b32 v138, v59, v43 offset0:204 offset1:220
	v_mfma_f32_16x16x32_bf16 v[44:47], v[36:39], v[8:11], 0
	v_mov_b32_e32 v40, 0
	v_mov_b32_e32 v41, 0
	v_mfma_f32_16x16x32_bf16 v[36:39], v[36:39], v[4:7], 0
	s_nop 7
	ds_write2_b32 v137, v44, v36 offset0:96 offset1:112
	ds_write2_b32 v137, v45, v37 offset0:228 offset1:244
	ds_write2_b32 v138, v46, v38 offset0:104 offset1:120
	ds_write2_b32 v138, v47, v39 offset0:236 offset1:252
	s_waitcnt lgkmcnt(0)
	ds_read2st64_b32 v[128:129], v140 offset0:42 offset1:43
	ds_read2st64_b32 v[124:125], v141 offset0:40 offset1:41
	ds_read2st64_b32 v[120:121], v146 offset0:38 offset1:39
	ds_read2st64_b32 v[114:115], v147 offset0:36 offset1:37
	ds_read2st64_b32 v[110:111], v148 offset0:34 offset1:35
	ds_read2st64_b32 v[104:105], v149 offset0:32 offset1:33
	ds_read2st64_b32 v[98:99], v150 offset0:30 offset1:31
	ds_read2st64_b32 v[92:93], v151 offset0:28 offset1:29
	ds_read2st64_b32 v[84:85], v152 offset0:26 offset1:27
	ds_read2st64_b32 v[78:79], v153 offset0:24 offset1:25
	ds_read2st64_b32 v[72:73], v154 offset0:22 offset1:23
	ds_read2st64_b32 v[66:67], v155 offset0:20 offset1:21
	ds_read2st64_b32 v[62:63], v156 offset0:18 offset1:19
	ds_read2st64_b32 v[58:59], v157 offset0:16 offset1:17
	ds_read2st64_b32 v[54:55], v158 offset0:14 offset1:15
	ds_read2st64_b32 v[50:51], v139 offset0:12 offset1:13
	s_waitcnt lgkmcnt(0)
	v_mov_b32_e32 v36, 0
	v_mov_b32_e32 v38, 0
	v_mov_b32_e32 v39, 0
	s_and_saveexec_b64 s[0:1], vcc
	ds_read_b128 v[38:41], v159 offset:768
	s_or_b64 exec, exec, s[0:1]
	s_waitcnt lgkmcnt(0)
	v_mfma_f32_16x16x32_bf16 v[42:45], v[38:41], v[32:35], 0
	v_mov_b32_e32 v37, 0
	v_mfma_f32_16x16x32_bf16 v[46:49], v[38:41], v[28:31], 0
	s_nop 7
	ds_write2_b32 v137, v42, v46 offset1:16
	ds_write2_b32 v137, v43, v47 offset0:132 offset1:148
	ds_write2_b32 v138, v44, v48 offset0:8 offset1:24
	v_mfma_f32_16x16x32_bf16 v[160:163], v[38:41], v[24:27], 0
	v_mfma_f32_16x16x32_bf16 v[164:167], v[38:41], v[16:19], 0
	ds_write2_b32 v138, v45, v49 offset0:140 offset1:156
	s_nop 6
	ds_write2_b32 v137, v160, v164 offset0:32 offset1:48
	ds_write2_b32 v137, v161, v165 offset0:164 offset1:180
	v_mfma_f32_16x16x32_bf16 v[168:171], v[38:41], v[20:23], 0
	v_mfma_f32_16x16x32_bf16 v[42:45], v[38:41], v[12:15], 0
	ds_write2_b32 v138, v162, v166 offset0:40 offset1:56
	ds_write2_b32 v138, v163, v167 offset0:172 offset1:188
	s_nop 5
	ds_write2_b32 v137, v168, v42 offset0:64 offset1:80
	ds_write2_b32 v137, v169, v43 offset0:196 offset1:212
	ds_write2_b32 v138, v170, v44 offset0:72 offset1:88
	ds_write2_b32 v138, v171, v45 offset0:204 offset1:220
	v_mfma_f32_16x16x32_bf16 v[46:49], v[38:41], v[8:11], 0
	v_mfma_f32_16x16x32_bf16 v[38:41], v[38:41], v[4:7], 0
	s_nop 7
	ds_write2_b32 v137, v46, v38 offset0:96 offset1:112
	ds_write2_b32 v137, v47, v39 offset0:228 offset1:244
	ds_write2_b32 v138, v48, v40 offset0:104 offset1:120
	ds_write2_b32 v138, v49, v41 offset0:236 offset1:252
	s_waitcnt lgkmcnt(0)
	ds_read2st64_b32 v[106:107], v140 offset0:42 offset1:43
	ds_read2st64_b32 v[100:101], v141 offset0:40 offset1:41
	ds_read2st64_b32 v[94:95], v146 offset0:38 offset1:39
	ds_read2st64_b32 v[88:89], v147 offset0:36 offset1:37
	ds_read2st64_b32 v[80:81], v148 offset0:34 offset1:35
	ds_read2st64_b32 v[74:75], v149 offset0:32 offset1:33
	ds_read2st64_b32 v[68:69], v150 offset0:30 offset1:31
	ds_read2st64_b32 v[64:65], v151 offset0:28 offset1:29
	ds_read2st64_b32 v[60:61], v152 offset0:26 offset1:27
	ds_read2st64_b32 v[56:57], v153 offset0:24 offset1:25
	ds_read2st64_b32 v[52:53], v154 offset0:22 offset1:23
	ds_read2st64_b32 v[48:49], v155 offset0:20 offset1:21
	ds_read2st64_b32 v[46:47], v156 offset0:18 offset1:19
	ds_read2st64_b32 v[44:45], v157 offset0:16 offset1:17
	ds_read2st64_b32 v[42:43], v158 offset0:14 offset1:15
	ds_read2st64_b32 v[40:41], v139 offset0:12 offset1:13
	s_waitcnt lgkmcnt(0)
	v_mov_b32_e32 v38, 0
	v_mov_b32_e32 v39, 0
	s_and_saveexec_b64 s[0:1], vcc
	s_cbranch_execz .LBB0_594
	ds_read_b128 v[36:39], v159
	s_branch .LBB0_594
